# all regular GEMM K-loops (P1 P2 P4 P9 P11 P12): A[x][0] LDS-DMA stage moved to the following 2-load segment, counted waits 8/6
# speedup vs baseline: 1.0065x; 1.0024x over previous
; #define PG8_STAGE(bufoff, gbase, voff) do { _Pragma("unroll") for (int _i = 0; _i < 2; ++_i) \
;         __builtin_amdgcn_global_load_lds((const unsigned*)((const char*)(gbase) + (voff)[_i]), (PG8_LAS unsigned*)(lds + (bufoff) + ldsw + _i * 8192), 16, 0, 0); } while (0)
; #define PG8_LDA(dst, b, h) do { _Pragma("unroll") for (int m = 0; m < 4; ++m) _Pragma("unroll") for (int k = 0; k < 2; ++k) dst[m][k] = *(const PG8_LAS bf16x8*)(lds + PG8_SA(b, h) + aoff + m * 2048 + k * 1024); } while (0)
; #define PG8_LDB(dst, b, h) do { _Pragma("unroll") for (int n = 0; n < 2; ++n) _Pragma("unroll") for (int k = 0; k < 2; ++k) dst[n][k] = *(const PG8_LAS bf16x8*)(lds + PG8_SB(b, h) + boff + n * 2048 + k * 1024); } while (0)
; #define PG8_MMA(ai, bj, At, Bt) do { __builtin_amdgcn_s_setprio(1); _Pragma("unroll") for (int m = 0; m < 4; ++m) _Pragma("unroll") for (int n = 0; n < 2; ++n) _Pragma("unroll") for (int k = 0; k < 2; ++k) \
;         acc[ai][bj][m][n] = __builtin_amdgcn_mfma_f32_16x16x32_bf16(Bt[n][k], At[m][k], acc[ai][bj][m][n], 0, 0, 0); __builtin_amdgcn_s_setprio(0); } while (0)
; #define PG8_WAIT_V(n) asm volatile("s_waitcnt vmcnt(" #n ")" ::: "memory")
; #define PG8_WAIT_L(n) asm volatile("s_waitcnt lgkmcnt(" #n ")" ::: "memory")
; #define PG8_BAR __builtin_amdgcn_s_barrier()
; #define PG8_SCHED __builtin_amdgcn_sched_barrier(0)
; template <class Epi, class Sched, bool ALIGN_EPI = false, bool SP2 = false>
; __device__ __forceinline__ void gemm_phase(PG8_LAS unsigned char* lds, const Gemm g, const Sched& S, const Epi& E) {
;     ...
;             const bool last = (t == nt - 2);
;             const char* a1 = cA + (size_t)(t + 1) * kstep;
;             const char* a2 = last ? nA : cA + (size_t)(t + 2) * kstep; const char* b2 = last ? nB : cB + (size_t)(t + 2) * kstep;
;             const char* a3 = a2 + kstep; const char* b3 = b2 + kstep;
;             if (last && has_next) S.a_ready(nxt);
;             if constexpr (SP2) {
;             PG8_LDB(B0, 0, 0); PG8_LDB(B1, 0, 1); PG8_SCHED; PG8_LDA(At, 0, 0); PG8_STAGE(PG8_SA(1, 1), a1 + hstep, voffA);
;             PG8_WAIT_V(8); PG8_WAIT_L(0); PG8_BAR; PG8_MMA(0, 0, At, B0); PG8_MMA(0, 1, At, B1); PG8_BAR; PG8_SCHED;
;             PG8_LDA(At, 0, 1); PG8_STAGE(PG8_SB(0, 0), b2, voffB); PG8_STAGE(PG8_SB(0, 1), b2 + hstep, voffB); PG8_STAGE(PG8_SA(0, 0), a2, voffA);
.LBB0_200:
	ds_read_b128 v[148:151], v154
	ds_read_b128 v[158:161], v154 offset:1024
	ds_read_b128 v[162:165], v154 offset:2048
	ds_read_b128 v[166:169], v154 offset:3072
	ds_read_b128 v[170:173], v155
	ds_read_b128 v[174:177], v155 offset:1024
	ds_read_b128 v[180:183], v155 offset:2048
	ds_read_b128 v[184:187], v155 offset:3072
	s_add_u32 s46, s44, 0x4000
	s_addc_u32 s47, s45, 0
	s_cmpk_eq_i32 s76, 0xa8
	s_cselect_b32 s50, s6, s46
	s_cselect_b32 s51, s7, s47
	s_cselect_b32 s48, s24, s74
	s_cselect_b32 s49, s25, s75
	s_sub_u32 s46, s44, 0x4000
	s_subb_u32 s47, s45, 0
	v_lshl_add_u64 v[224:225], s[46:47], 0, v[130:131]
	s_mov_b32 m0, s57
	s_nop 0
	global_load_lds_dwordx4 v[224:225], off
	v_lshl_add_u64 v[224:225], s[46:47], 0, v[134:135]
	s_mov_b32 m0, s58
	s_nop 0
	global_load_lds_dwordx4 v[224:225], off
	v_lshl_add_u64 v[224:225], s[44:45], 0, v[140:141]
	s_add_i32 m0, s26, 0xc000
	ds_read_b128 v[188:191], v156
	ds_read_b128 v[196:199], v156 offset:1024
	ds_read_b128 v[200:203], v156 offset:2048
	ds_read_b128 v[204:207], v156 offset:3072
	ds_read_b128 v[208:211], v156 offset:4096
	ds_read_b128 v[212:215], v156 offset:5120
	ds_read_b128 v[216:219], v156 offset:6144
	ds_read_b128 v[220:223], v156 offset:7168
	global_load_lds_dwordx4 v[224:225], off
	v_lshl_add_u64 v[224:225], s[44:45], 0, v[142:143]
	s_add_i32 m0, s26, 0xe000
	s_nop 0
	global_load_lds_dwordx4 v[224:225], off
	s_waitcnt vmcnt(8)
	s_waitcnt lgkmcnt(0)
	s_barrier
	s_setprio 1
	s_waitcnt lgkmcnt(0)
	v_mfma_f32_16x16x32_bf16 v[126:129], v[148:151], v[188:191], v[126:129]
	v_mfma_f32_16x16x32_bf16 v[122:125], v[162:165], v[188:191], v[122:125]
	v_mfma_f32_16x16x32_bf16 v[110:113], v[148:151], v[200:203], v[110:113]
	v_mfma_f32_16x16x32_bf16 v[106:109], v[162:165], v[200:203], v[106:109]
	v_mfma_f32_16x16x32_bf16 v[94:97], v[148:151], v[208:211], v[94:97]
	v_mfma_f32_16x16x32_bf16 v[90:93], v[162:165], v[208:211], v[90:93]
	v_mfma_f32_16x16x32_bf16 v[78:81], v[148:151], v[216:219], v[78:81]
	v_mfma_f32_16x16x32_bf16 v[74:77], v[162:165], v[216:219], v[74:77]
	v_mfma_f32_16x16x32_bf16 v[126:129], v[158:161], v[196:199], v[126:129]
	v_mfma_f32_16x16x32_bf16 v[122:125], v[166:169], v[196:199], v[122:125]
	v_mfma_f32_16x16x32_bf16 v[110:113], v[158:161], v[204:207], v[110:113]
	v_mfma_f32_16x16x32_bf16 v[106:109], v[166:169], v[204:207], v[106:109]
	v_mfma_f32_16x16x32_bf16 v[94:97], v[158:161], v[212:215], v[94:97]
	v_mfma_f32_16x16x32_bf16 v[90:93], v[166:169], v[212:215], v[90:93]
	v_mfma_f32_16x16x32_bf16 v[78:81], v[158:161], v[220:223], v[78:81]
	v_mfma_f32_16x16x32_bf16 v[74:77], v[166:169], v[220:223], v[74:77]
	s_setprio 0
	s_setprio 1
	v_mfma_f32_16x16x32_bf16 v[118:121], v[170:173], v[188:191], v[118:121]
	v_mfma_f32_16x16x32_bf16 v[114:117], v[180:183], v[188:191], v[114:117]
	v_mfma_f32_16x16x32_bf16 v[102:105], v[170:173], v[200:203], v[102:105]
	v_mfma_f32_16x16x32_bf16 v[98:101], v[180:183], v[200:203], v[98:101]
	v_mfma_f32_16x16x32_bf16 v[86:89], v[170:173], v[208:211], v[86:89]
	v_mfma_f32_16x16x32_bf16 v[82:85], v[180:183], v[208:211], v[82:85]
	v_mfma_f32_16x16x32_bf16 v[70:73], v[170:173], v[216:219], v[70:73]
	v_mfma_f32_16x16x32_bf16 v[66:69], v[180:183], v[216:219], v[66:69]
	v_mfma_f32_16x16x32_bf16 v[118:121], v[174:177], v[196:199], v[118:121]
	v_mfma_f32_16x16x32_bf16 v[114:117], v[184:187], v[196:199], v[114:117]
	v_mfma_f32_16x16x32_bf16 v[102:105], v[174:177], v[204:207], v[102:105]
	v_mfma_f32_16x16x32_bf16 v[98:101], v[184:187], v[204:207], v[98:101]
	v_mfma_f32_16x16x32_bf16 v[86:89], v[174:177], v[212:215], v[86:89]
	v_mfma_f32_16x16x32_bf16 v[82:85], v[184:187], v[212:215], v[82:85]
	v_mfma_f32_16x16x32_bf16 v[70:73], v[174:177], v[220:223], v[70:73]
	v_mfma_f32_16x16x32_bf16 v[66:69], v[184:187], v[220:223], v[66:69]
	s_setprio 0
	s_barrier
	s_add_i32 s77, s59, s3
	v_lshl_add_u64 v[224:225], s[48:49], 0, v[132:133]
	s_mov_b32 m0, s77
	ds_read_b128 v[188:191], v156 offset:16384
	ds_read_b128 v[196:199], v156 offset:17408
	ds_read_b128 v[200:203], v156 offset:18432
	ds_read_b128 v[204:207], v156 offset:19456
	ds_read_b128 v[208:211], v156 offset:20480
	ds_read_b128 v[212:215], v156 offset:21504
	ds_read_b128 v[216:219], v156 offset:22528
	ds_read_b128 v[220:223], v156 offset:23552
	global_load_lds_dwordx4 v[224:225], off
	s_add_i32 m0, s77, 0x2000
	s_add_u32 s78, s48, 0x4000
	v_lshl_add_u64 v[224:225], s[48:49], 0, v[136:137]
	s_addc_u32 s79, s49, 0
	s_add_i32 s77, s61, s3
	global_load_lds_dwordx4 v[224:225], off
	v_lshl_add_u64 v[224:225], s[78:79], 0, v[132:133]
	s_mov_b32 m0, s77
	s_nop 0
	global_load_lds_dwordx4 v[224:225], off
	v_lshl_add_u64 v[224:225], s[78:79], 0, v[136:137]
	s_add_i32 m0, s77, 0x2000
	s_nop 0
	global_load_lds_dwordx4 v[224:225], off
	s_waitcnt vmcnt(6)
	s_waitcnt lgkmcnt(0)
	s_barrier
; #define PG8_STAGE(bufoff, gbase, voff) do { _Pragma("unroll") for (int _i = 0; _i < 2; ++_i) \
;         __builtin_amdgcn_global_load_lds((const unsigned*)((const char*)(gbase) + (voff)[_i]), (PG8_LAS unsigned*)(lds + (bufoff) + ldsw + _i * 8192), 16, 0, 0); } while (0)
; #define PG8_LDA(dst, b, h) do { _Pragma("unroll") for (int m = 0; m < 4; ++m) _Pragma("unroll") for (int k = 0; k < 2; ++k) dst[m][k] = *(const PG8_LAS bf16x8*)(lds + PG8_SA(b, h) + aoff + m * 2048 + k * 1024); } while (0)
; #define PG8_LDB(dst, b, h) do { _Pragma("unroll") for (int n = 0; n < 2; ++n) _Pragma("unroll") for (int k = 0; k < 2; ++k) dst[n][k] = *(const PG8_LAS bf16x8*)(lds + PG8_SB(b, h) + boff + n * 2048 + k * 1024); } while (0)
; #define PG8_MMA(ai, bj, At, Bt) do { __builtin_amdgcn_s_setprio(1); _Pragma("unroll") for (int m = 0; m < 4; ++m) _Pragma("unroll") for (int n = 0; n < 2; ++n) _Pragma("unroll") for (int k = 0; k < 2; ++k) \
;         acc[ai][bj][m][n] = __builtin_amdgcn_mfma_f32_16x16x32_bf16(Bt[n][k], At[m][k], acc[ai][bj][m][n], 0, 0, 0); __builtin_amdgcn_s_setprio(0); } while (0)
; #define PG8_WAIT_V(n) asm volatile("s_waitcnt vmcnt(" #n ")" ::: "memory")
; #define PG8_WAIT_L(n) asm volatile("s_waitcnt lgkmcnt(" #n ")" ::: "memory")
; #define PG8_BAR __builtin_amdgcn_s_barrier()
; #define PG8_SCHED __builtin_amdgcn_sched_barrier(0)
; template <class Epi, class Sched, bool ALIGN_EPI = false, bool SP2 = false>
; __device__ __forceinline__ void gemm_phase(PG8_LAS unsigned char* lds, const Gemm g, const Sched& S, const Epi& E) {
;     ...
;             PG8_LDA(At, 0, 1); PG8_STAGE(PG8_SB(0, 0), b2, voffB); PG8_STAGE(PG8_SB(0, 1), b2 + hstep, voffB); PG8_STAGE(PG8_SA(0, 0), a2, voffA);
;             PG8_WAIT_V(8); PG8_WAIT_L(0); PG8_BAR; PG8_MMA(1, 0, At, B0); PG8_MMA(1, 1, At, B1); PG8_BAR; PG8_SCHED;
;             PG8_LDB(B0, 1, 0); PG8_LDB(B1, 1, 1); PG8_SCHED; PG8_LDA(At, 1, 0); PG8_STAGE(PG8_SA(0, 1), a2 + hstep, voffA);
	s_setprio 1
	s_waitcnt lgkmcnt(0)
	v_mfma_f32_16x16x32_bf16 v[62:65], v[148:151], v[188:191], v[62:65]
	v_mfma_f32_16x16x32_bf16 v[58:61], v[162:165], v[188:191], v[58:61]
	v_mfma_f32_16x16x32_bf16 v[46:49], v[148:151], v[200:203], v[46:49]
	v_mfma_f32_16x16x32_bf16 v[42:45], v[162:165], v[200:203], v[42:45]
	v_mfma_f32_16x16x32_bf16 v[30:33], v[148:151], v[208:211], v[30:33]
	v_mfma_f32_16x16x32_bf16 v[26:29], v[162:165], v[208:211], v[26:29]
	v_mfma_f32_16x16x32_bf16 v[14:17], v[148:151], v[216:219], v[14:17]
	v_mfma_f32_16x16x32_bf16 v[10:13], v[162:165], v[216:219], v[10:13]
	v_mfma_f32_16x16x32_bf16 v[62:65], v[158:161], v[196:199], v[62:65]
	v_mfma_f32_16x16x32_bf16 v[58:61], v[166:169], v[196:199], v[58:61]
	v_mfma_f32_16x16x32_bf16 v[46:49], v[158:161], v[204:207], v[46:49]
	v_mfma_f32_16x16x32_bf16 v[42:45], v[166:169], v[204:207], v[42:45]
	v_mfma_f32_16x16x32_bf16 v[30:33], v[158:161], v[212:215], v[30:33]
	v_mfma_f32_16x16x32_bf16 v[26:29], v[166:169], v[212:215], v[26:29]
	v_mfma_f32_16x16x32_bf16 v[14:17], v[158:161], v[220:223], v[14:17]
	v_mfma_f32_16x16x32_bf16 v[10:13], v[166:169], v[220:223], v[10:13]
	s_setprio 0
	s_setprio 1
	v_mfma_f32_16x16x32_bf16 v[54:57], v[170:173], v[188:191], v[54:57]
	v_mfma_f32_16x16x32_bf16 v[50:53], v[180:183], v[188:191], v[50:53]
	v_mfma_f32_16x16x32_bf16 v[38:41], v[170:173], v[200:203], v[38:41]
	v_mfma_f32_16x16x32_bf16 v[34:37], v[180:183], v[200:203], v[34:37]
	v_mfma_f32_16x16x32_bf16 v[22:25], v[170:173], v[208:211], v[22:25]
	v_mfma_f32_16x16x32_bf16 v[18:21], v[180:183], v[208:211], v[18:21]
	v_mfma_f32_16x16x32_bf16 v[6:9], v[170:173], v[216:219], v[6:9]
	v_mfma_f32_16x16x32_bf16 v[2:5], v[180:183], v[216:219], v[2:5]
	v_mfma_f32_16x16x32_bf16 v[54:57], v[174:177], v[196:199], v[54:57]
	v_mfma_f32_16x16x32_bf16 v[50:53], v[184:187], v[196:199], v[50:53]
	v_mfma_f32_16x16x32_bf16 v[38:41], v[174:177], v[204:207], v[38:41]
	v_mfma_f32_16x16x32_bf16 v[34:37], v[184:187], v[204:207], v[34:37]
	v_mfma_f32_16x16x32_bf16 v[22:25], v[174:177], v[212:215], v[22:25]
	v_mfma_f32_16x16x32_bf16 v[18:21], v[184:187], v[212:215], v[18:21]
	v_mfma_f32_16x16x32_bf16 v[6:9], v[174:177], v[220:223], v[6:9]
	v_mfma_f32_16x16x32_bf16 v[2:5], v[184:187], v[220:223], v[2:5]
	s_setprio 0
	s_barrier
	s_add_i32 s77, 0, 0x18000
	v_add_u32_e32 v138, s77, v153
	s_add_i32 s78, 0, 0x1c000
	ds_read_b128 v[148:151], v138
	ds_read_b128 v[158:161], v138 offset:1024
	ds_read_b128 v[162:165], v138 offset:2048
	ds_read_b128 v[166:169], v138 offset:3072
	v_add_u32_e32 v138, s78, v153
	ds_read_b128 v[170:173], v138
	ds_read_b128 v[174:177], v138 offset:1024
	ds_read_b128 v[180:183], v138 offset:2048
	ds_read_b128 v[184:187], v138 offset:3072
	v_lshl_add_u64 v[224:225], s[50:51], 0, v[130:131]
	s_mov_b32 m0, s26
	s_nop 0
	global_load_lds_dwordx4 v[224:225], off
	v_lshl_add_u64 v[224:225], s[50:51], 0, v[134:135]
	s_mov_b32 m0, s27
	s_nop 0
	global_load_lds_dwordx4 v[224:225], off
	s_add_u32 s50, s50, 0x4000
	s_addc_u32 s51, s51, 0
	s_mov_b32 m0, s28
	v_lshl_add_u64 v[224:225], s[50:51], 0, v[130:131]
	ds_read_b128 v[188:191], v156 offset:32768
	ds_read_b128 v[196:199], v156 offset:33792
	ds_read_b128 v[200:203], v156 offset:34816
	ds_read_b128 v[204:207], v156 offset:35840
	ds_read_b128 v[208:211], v156 offset:36864
	ds_read_b128 v[212:215], v156 offset:37888
	ds_read_b128 v[216:219], v156 offset:38912
	ds_read_b128 v[220:223], v156 offset:39936
	global_load_lds_dwordx4 v[224:225], off
	v_lshl_add_u64 v[224:225], s[50:51], 0, v[134:135]
	s_mov_b32 m0, s29
	s_nop 0
	global_load_lds_dwordx4 v[224:225], off
	s_waitcnt vmcnt(8)
	s_waitcnt lgkmcnt(0)
	s_barrier
; #define PG8_STAGE(bufoff, gbase, voff) do { _Pragma("unroll") for (int _i = 0; _i < 2; ++_i) \
;         __builtin_amdgcn_global_load_lds((const unsigned*)((const char*)(gbase) + (voff)[_i]), (PG8_LAS unsigned*)(lds + (bufoff) + ldsw + _i * 8192), 16, 0, 0); } while (0)
; #define PG8_LDA(dst, b, h) do { _Pragma("unroll") for (int m = 0; m < 4; ++m) _Pragma("unroll") for (int k = 0; k < 2; ++k) dst[m][k] = *(const PG8_LAS bf16x8*)(lds + PG8_SA(b, h) + aoff + m * 2048 + k * 1024); } while (0)
; #define PG8_MMA(ai, bj, At, Bt) do { __builtin_amdgcn_s_setprio(1); _Pragma("unroll") for (int m = 0; m < 4; ++m) _Pragma("unroll") for (int n = 0; n < 2; ++n) _Pragma("unroll") for (int k = 0; k < 2; ++k) \
;         acc[ai][bj][m][n] = __builtin_amdgcn_mfma_f32_16x16x32_bf16(Bt[n][k], At[m][k], acc[ai][bj][m][n], 0, 0, 0); __builtin_amdgcn_s_setprio(0); } while (0)
; #define PG8_WAIT_V(n) asm volatile("s_waitcnt vmcnt(" #n ")" ::: "memory")
; #define PG8_WAIT_L(n) asm volatile("s_waitcnt lgkmcnt(" #n ")" ::: "memory")
; #define PG8_BAR __builtin_amdgcn_s_barrier()
; #define PG8_SCHED __builtin_amdgcn_sched_barrier(0)
; template <class Epi, class Sched, bool ALIGN_EPI = false, bool SP2 = false>
; __device__ __forceinline__ void gemm_phase(PG8_LAS unsigned char* lds, const Gemm g, const Sched& S, const Epi& E) {
;     ...
;             PG8_WAIT_V(8); PG8_WAIT_L(0); PG8_BAR; PG8_MMA(0, 0, At, B0); PG8_MMA(0, 1, At, B1); PG8_BAR; PG8_SCHED;
;             PG8_LDA(At, 1, 1); PG8_STAGE(PG8_SB(1, 0), b3, voffB); PG8_STAGE(PG8_SB(1, 1), b3 + hstep, voffB); PG8_STAGE(PG8_SA(1, 0), a3, voffA);
;             PG8_WAIT_V(8); PG8_WAIT_L(0); PG8_BAR; PG8_MMA(1, 0, At, B0); PG8_MMA(1, 1, At, B1); PG8_BAR; PG8_SCHED;
;     ...
;         if constexpr (ALIGN_EPI) { if (wr == 0) PG8_BAR; }
	s_setprio 1
	s_waitcnt lgkmcnt(0)
	v_mfma_f32_16x16x32_bf16 v[126:129], v[148:151], v[188:191], v[126:129]
	v_mfma_f32_16x16x32_bf16 v[122:125], v[162:165], v[188:191], v[122:125]
	v_mfma_f32_16x16x32_bf16 v[110:113], v[148:151], v[200:203], v[110:113]
	v_mfma_f32_16x16x32_bf16 v[106:109], v[162:165], v[200:203], v[106:109]
	v_mfma_f32_16x16x32_bf16 v[94:97], v[148:151], v[208:211], v[94:97]
	v_mfma_f32_16x16x32_bf16 v[90:93], v[162:165], v[208:211], v[90:93]
	v_mfma_f32_16x16x32_bf16 v[78:81], v[148:151], v[216:219], v[78:81]
	v_mfma_f32_16x16x32_bf16 v[74:77], v[162:165], v[216:219], v[74:77]
	v_mfma_f32_16x16x32_bf16 v[126:129], v[158:161], v[196:199], v[126:129]
	v_mfma_f32_16x16x32_bf16 v[122:125], v[166:169], v[196:199], v[122:125]
	v_mfma_f32_16x16x32_bf16 v[110:113], v[158:161], v[204:207], v[110:113]
	v_mfma_f32_16x16x32_bf16 v[106:109], v[166:169], v[204:207], v[106:109]
	v_mfma_f32_16x16x32_bf16 v[94:97], v[158:161], v[212:215], v[94:97]
	v_mfma_f32_16x16x32_bf16 v[90:93], v[166:169], v[212:215], v[90:93]
	v_mfma_f32_16x16x32_bf16 v[78:81], v[158:161], v[220:223], v[78:81]
	v_mfma_f32_16x16x32_bf16 v[74:77], v[166:169], v[220:223], v[74:77]
	s_setprio 0
	s_setprio 1
	v_mfma_f32_16x16x32_bf16 v[118:121], v[170:173], v[188:191], v[118:121]
	v_mfma_f32_16x16x32_bf16 v[114:117], v[180:183], v[188:191], v[114:117]
	v_mfma_f32_16x16x32_bf16 v[102:105], v[170:173], v[200:203], v[102:105]
	v_mfma_f32_16x16x32_bf16 v[98:101], v[180:183], v[200:203], v[98:101]
	v_mfma_f32_16x16x32_bf16 v[86:89], v[170:173], v[208:211], v[86:89]
	v_mfma_f32_16x16x32_bf16 v[82:85], v[180:183], v[208:211], v[82:85]
	v_mfma_f32_16x16x32_bf16 v[70:73], v[170:173], v[216:219], v[70:73]
	v_mfma_f32_16x16x32_bf16 v[66:69], v[180:183], v[216:219], v[66:69]
	v_mfma_f32_16x16x32_bf16 v[118:121], v[174:177], v[196:199], v[118:121]
	v_mfma_f32_16x16x32_bf16 v[114:117], v[184:187], v[196:199], v[114:117]
	v_mfma_f32_16x16x32_bf16 v[102:105], v[174:177], v[204:207], v[102:105]
	v_mfma_f32_16x16x32_bf16 v[98:101], v[184:187], v[204:207], v[98:101]
	v_mfma_f32_16x16x32_bf16 v[86:89], v[174:177], v[212:215], v[86:89]
	v_mfma_f32_16x16x32_bf16 v[82:85], v[184:187], v[212:215], v[82:85]
	v_mfma_f32_16x16x32_bf16 v[70:73], v[174:177], v[220:223], v[70:73]
	v_mfma_f32_16x16x32_bf16 v[66:69], v[184:187], v[220:223], v[66:69]
	s_setprio 0
	s_barrier
	s_add_u32 s50, s48, 0x8000
	s_addc_u32 s51, s49, 0
	s_add_i32 s77, s77, s3
	v_lshl_add_u64 v[224:225], s[50:51], 0, v[132:133]
	s_mov_b32 m0, s77
	ds_read_b128 v[188:191], v156 offset:49152
	ds_read_b128 v[196:199], v156 offset:50176
	ds_read_b128 v[200:203], v156 offset:51200
	ds_read_b128 v[204:207], v156 offset:52224
	ds_read_b128 v[208:211], v156 offset:53248
	ds_read_b128 v[212:215], v156 offset:54272
	ds_read_b128 v[216:219], v156 offset:55296
	ds_read_b128 v[220:223], v156 offset:56320
	global_load_lds_dwordx4 v[224:225], off
	s_add_i32 m0, s77, 0x2000
	s_add_u32 s48, s48, 0xc000
	v_lshl_add_u64 v[224:225], s[50:51], 0, v[136:137]
	s_addc_u32 s49, s49, 0
	s_add_i32 s50, s78, s3
	global_load_lds_dwordx4 v[224:225], off
	v_lshl_add_u64 v[224:225], s[48:49], 0, v[132:133]
	s_mov_b32 m0, s50
	s_nop 0
	global_load_lds_dwordx4 v[224:225], off
	v_lshl_add_u64 v[224:225], s[48:49], 0, v[136:137]
	s_add_i32 m0, s50, 0x2000
	s_nop 0
	global_load_lds_dwordx4 v[224:225], off
	s_waitcnt vmcnt(6)
	s_waitcnt lgkmcnt(0)
	s_barrier
	s_setprio 1
	s_waitcnt lgkmcnt(0)
	v_mfma_f32_16x16x32_bf16 v[62:65], v[148:151], v[188:191], v[62:65]
	v_mfma_f32_16x16x32_bf16 v[58:61], v[162:165], v[188:191], v[58:61]
	v_mfma_f32_16x16x32_bf16 v[46:49], v[148:151], v[200:203], v[46:49]
	v_mfma_f32_16x16x32_bf16 v[42:45], v[162:165], v[200:203], v[42:45]
	v_mfma_f32_16x16x32_bf16 v[30:33], v[148:151], v[208:211], v[30:33]
	v_mfma_f32_16x16x32_bf16 v[26:29], v[162:165], v[208:211], v[26:29]
	v_mfma_f32_16x16x32_bf16 v[14:17], v[148:151], v[216:219], v[14:17]
	v_mfma_f32_16x16x32_bf16 v[10:13], v[162:165], v[216:219], v[10:13]
	v_mfma_f32_16x16x32_bf16 v[62:65], v[158:161], v[196:199], v[62:65]
	v_mfma_f32_16x16x32_bf16 v[58:61], v[166:169], v[196:199], v[58:61]
	v_mfma_f32_16x16x32_bf16 v[46:49], v[158:161], v[204:207], v[46:49]
	v_mfma_f32_16x16x32_bf16 v[42:45], v[166:169], v[204:207], v[42:45]
	v_mfma_f32_16x16x32_bf16 v[30:33], v[158:161], v[212:215], v[30:33]
	v_mfma_f32_16x16x32_bf16 v[26:29], v[166:169], v[212:215], v[26:29]
	v_mfma_f32_16x16x32_bf16 v[14:17], v[158:161], v[220:223], v[14:17]
	v_mfma_f32_16x16x32_bf16 v[10:13], v[166:169], v[220:223], v[10:13]
	s_setprio 0
	s_setprio 1
	v_mfma_f32_16x16x32_bf16 v[54:57], v[170:173], v[188:191], v[54:57]
	v_mfma_f32_16x16x32_bf16 v[50:53], v[180:183], v[188:191], v[50:53]
	v_mfma_f32_16x16x32_bf16 v[38:41], v[170:173], v[200:203], v[38:41]
	v_mfma_f32_16x16x32_bf16 v[34:37], v[180:183], v[200:203], v[34:37]
	v_mfma_f32_16x16x32_bf16 v[22:25], v[170:173], v[208:211], v[22:25]
	v_mfma_f32_16x16x32_bf16 v[18:21], v[180:183], v[208:211], v[18:21]
	v_mfma_f32_16x16x32_bf16 v[6:9], v[170:173], v[216:219], v[6:9]
	v_mfma_f32_16x16x32_bf16 v[2:5], v[180:183], v[216:219], v[2:5]
	v_mfma_f32_16x16x32_bf16 v[54:57], v[174:177], v[196:199], v[54:57]
	v_mfma_f32_16x16x32_bf16 v[50:53], v[184:187], v[196:199], v[50:53]
	v_mfma_f32_16x16x32_bf16 v[38:41], v[174:177], v[204:207], v[38:41]
	v_mfma_f32_16x16x32_bf16 v[34:37], v[184:187], v[204:207], v[34:37]
	v_mfma_f32_16x16x32_bf16 v[22:25], v[174:177], v[212:215], v[22:25]
	v_mfma_f32_16x16x32_bf16 v[18:21], v[184:187], v[212:215], v[18:21]
	v_mfma_f32_16x16x32_bf16 v[6:9], v[174:177], v[220:223], v[6:9]
	v_mfma_f32_16x16x32_bf16 v[2:5], v[184:187], v[220:223], v[2:5]
	s_setprio 0
	s_barrier
	s_add_i32 s76, s76, 2
	s_add_u32 s44, s44, 0x10000
	s_addc_u32 s45, s45, 0
	s_add_u32 s74, s74, 0x10000
	s_addc_u32 s75, s75, 0
	s_cmpk_gt_u32 s76, 0xa9
	s_cbranch_scc0 .LBB0_200
	s_and_b64 vcc, exec, s[18:19]
	s_cbranch_vccz .LBB0_203
	s_barrier

; #define PG8_STAGE(bufoff, gbase, voff) do { _Pragma("unroll") for (int _i = 0; _i < 2; ++_i) \
;         __builtin_amdgcn_global_load_lds((const unsigned*)((const char*)(gbase) + (voff)[_i]), (PG8_LAS unsigned*)(lds + (bufoff) + ldsw + _i * 8192), 16, 0, 0); } while (0)
; #define PG8_LDA(dst, b, h) do { _Pragma("unroll") for (int m = 0; m < 4; ++m) _Pragma("unroll") for (int k = 0; k < 2; ++k) dst[m][k] = *(const PG8_LAS bf16x8*)(lds + PG8_SA(b, h) + aoff + m * 2048 + k * 1024); } while (0)
; #define PG8_LDB(dst, b, h) do { _Pragma("unroll") for (int n = 0; n < 2; ++n) _Pragma("unroll") for (int k = 0; k < 2; ++k) dst[n][k] = *(const PG8_LAS bf16x8*)(lds + PG8_SB(b, h) + boff + n * 2048 + k * 1024); } while (0)
; #define PG8_MMA(ai, bj, At, Bt) do { __builtin_amdgcn_s_setprio(1); _Pragma("unroll") for (int m = 0; m < 4; ++m) _Pragma("unroll") for (int n = 0; n < 2; ++n) _Pragma("unroll") for (int k = 0; k < 2; ++k) \
;         acc[ai][bj][m][n] = __builtin_amdgcn_mfma_f32_16x16x32_bf16(Bt[n][k], At[m][k], acc[ai][bj][m][n], 0, 0, 0); __builtin_amdgcn_s_setprio(0); } while (0)
; #define PG8_WAIT_V(n) asm volatile("s_waitcnt vmcnt(" #n ")" ::: "memory")
; #define PG8_WAIT_L(n) asm volatile("s_waitcnt lgkmcnt(" #n ")" ::: "memory")
; #define PG8_BAR __builtin_amdgcn_s_barrier()
; #define PG8_SCHED __builtin_amdgcn_sched_barrier(0)
; template <class Epi, class Sched, bool ALIGN_EPI = false, bool SP2 = false>
; __device__ __forceinline__ void gemm_phase(PG8_LAS unsigned char* lds, const Gemm g, const Sched& S, const Epi& E) {
;     ...
;             const bool last = (t == nt - 2);
;             const char* a1 = cA + (size_t)(t + 1) * kstep;
;             const char* a2 = last ? nA : cA + (size_t)(t + 2) * kstep; const char* b2 = last ? nB : cB + (size_t)(t + 2) * kstep;
;             const char* a3 = a2 + kstep; const char* b3 = b2 + kstep;
;             if (last && has_next) S.a_ready(nxt);
;             if constexpr (SP2) {
;             PG8_LDB(B0, 0, 0); PG8_LDB(B1, 0, 1); PG8_SCHED; PG8_LDA(At, 0, 0); PG8_STAGE(PG8_SA(1, 1), a1 + hstep, voffA);
;             PG8_WAIT_V(8); PG8_WAIT_L(0); PG8_BAR; PG8_MMA(0, 0, At, B0); PG8_MMA(0, 1, At, B1); PG8_BAR; PG8_SCHED;
;             PG8_LDA(At, 0, 1); PG8_STAGE(PG8_SB(0, 0), b2, voffB); PG8_STAGE(PG8_SB(0, 1), b2 + hstep, voffB); PG8_STAGE(PG8_SA(0, 0), a2, voffA);
.LBB0_290:
	ds_read_b128 v[146:149], v162
	ds_read_b128 v[150:153], v162 offset:1024
	ds_read_b128 v[154:157], v162 offset:2048
	ds_read_b128 v[168:171], v162 offset:3072
	ds_read_b128 v[172:175], v163
	ds_read_b128 v[180:183], v163 offset:1024
	ds_read_b128 v[184:187], v163 offset:2048
	ds_read_b128 v[188:191], v163 offset:3072
	s_add_u32 s59, s72, 0x4000
	s_addc_u32 s62, s73, 0
	s_cmp_eq_u32 s58, 60
	s_cselect_b32 s78, s19, s59
	s_cselect_b32 s79, s5, s62
	s_cselect_b32 s76, s26, s33
	s_cselect_b32 s77, s17, s56
	s_sub_u32 s74, s72, 0x4000
	s_subb_u32 s75, s73, 0
	v_lshl_add_u64 v[158:159], s[74:75], 0, v[130:131]
	s_mov_b32 m0, s51
	s_nop 0
	global_load_lds_dwordx4 v[158:159], off
	v_lshl_add_u64 v[158:159], s[74:75], 0, v[134:135]
	s_mov_b32 m0, s57
	s_nop 0
	global_load_lds_dwordx4 v[158:159], off
	v_lshl_add_u64 v[158:159], s[72:73], 0, v[138:139]
	s_add_i32 m0, s15, 0xc000
	ds_read_b128 v[198:201], v164
	ds_read_b128 v[202:205], v164 offset:1024
	ds_read_b128 v[206:209], v164 offset:2048
	ds_read_b128 v[210:213], v164 offset:3072
	ds_read_b128 v[214:217], v164 offset:4096
	ds_read_b128 v[218:221], v164 offset:5120
	ds_read_b128 v[222:225], v164 offset:6144
	ds_read_b128 v[226:229], v164 offset:7168
	global_load_lds_dwordx4 v[158:159], off
	v_lshl_add_u64 v[158:159], s[72:73], 0, v[140:141]
	s_add_i32 m0, s15, 0xe000
	s_nop 0
	global_load_lds_dwordx4 v[158:159], off
	s_waitcnt vmcnt(8)
	s_waitcnt lgkmcnt(0)
	s_barrier
	s_setprio 1
	s_waitcnt lgkmcnt(0)
	v_mfma_f32_16x16x32_bf16 v[126:129], v[146:149], v[198:201], v[126:129]
	v_mfma_f32_16x16x32_bf16 v[122:125], v[154:157], v[198:201], v[122:125]
	v_mfma_f32_16x16x32_bf16 v[110:113], v[146:149], v[206:209], v[110:113]
	v_mfma_f32_16x16x32_bf16 v[106:109], v[154:157], v[206:209], v[106:109]
	v_mfma_f32_16x16x32_bf16 v[94:97], v[146:149], v[214:217], v[94:97]
	v_mfma_f32_16x16x32_bf16 v[90:93], v[154:157], v[214:217], v[90:93]
	v_mfma_f32_16x16x32_bf16 v[78:81], v[146:149], v[222:225], v[78:81]
	v_mfma_f32_16x16x32_bf16 v[74:77], v[154:157], v[222:225], v[74:77]
	v_mfma_f32_16x16x32_bf16 v[126:129], v[150:153], v[202:205], v[126:129]
	v_mfma_f32_16x16x32_bf16 v[122:125], v[168:171], v[202:205], v[122:125]
	v_mfma_f32_16x16x32_bf16 v[110:113], v[150:153], v[210:213], v[110:113]
	v_mfma_f32_16x16x32_bf16 v[106:109], v[168:171], v[210:213], v[106:109]
	v_mfma_f32_16x16x32_bf16 v[94:97], v[150:153], v[218:221], v[94:97]
	v_mfma_f32_16x16x32_bf16 v[90:93], v[168:171], v[218:221], v[90:93]
	v_mfma_f32_16x16x32_bf16 v[78:81], v[150:153], v[226:229], v[78:81]
	v_mfma_f32_16x16x32_bf16 v[74:77], v[168:171], v[226:229], v[74:77]
	s_setprio 0
	s_setprio 1
	v_mfma_f32_16x16x32_bf16 v[118:121], v[172:175], v[198:201], v[118:121]
	v_mfma_f32_16x16x32_bf16 v[114:117], v[184:187], v[198:201], v[114:117]
	v_mfma_f32_16x16x32_bf16 v[102:105], v[172:175], v[206:209], v[102:105]
	v_mfma_f32_16x16x32_bf16 v[98:101], v[184:187], v[206:209], v[98:101]
	v_mfma_f32_16x16x32_bf16 v[86:89], v[172:175], v[214:217], v[86:89]
	v_mfma_f32_16x16x32_bf16 v[82:85], v[184:187], v[214:217], v[82:85]
	v_mfma_f32_16x16x32_bf16 v[70:73], v[172:175], v[222:225], v[70:73]
	v_mfma_f32_16x16x32_bf16 v[66:69], v[184:187], v[222:225], v[66:69]
	v_mfma_f32_16x16x32_bf16 v[118:121], v[180:183], v[202:205], v[118:121]
	v_mfma_f32_16x16x32_bf16 v[114:117], v[188:191], v[202:205], v[114:117]
	v_mfma_f32_16x16x32_bf16 v[102:105], v[180:183], v[210:213], v[102:105]
	v_mfma_f32_16x16x32_bf16 v[98:101], v[188:191], v[210:213], v[98:101]
	v_mfma_f32_16x16x32_bf16 v[86:89], v[180:183], v[218:221], v[86:89]
	v_mfma_f32_16x16x32_bf16 v[82:85], v[188:191], v[218:221], v[82:85]
	v_mfma_f32_16x16x32_bf16 v[70:73], v[180:183], v[226:229], v[70:73]
	v_mfma_f32_16x16x32_bf16 v[66:69], v[188:191], v[226:229], v[66:69]
	s_setprio 0
	s_barrier
	s_add_i32 s59, s81, s3
	v_lshl_add_u64 v[158:159], s[76:77], 0, v[132:133]
	s_mov_b32 m0, s59
	ds_read_b128 v[198:201], v164 offset:16384
	ds_read_b128 v[202:205], v164 offset:17408
	ds_read_b128 v[206:209], v164 offset:18432
	ds_read_b128 v[210:213], v164 offset:19456
	ds_read_b128 v[214:217], v164 offset:20480
	ds_read_b128 v[218:221], v164 offset:21504
	ds_read_b128 v[222:225], v164 offset:22528
	ds_read_b128 v[226:229], v164 offset:23552
	global_load_lds_dwordx4 v[158:159], off
	s_add_i32 m0, s59, 0x2000
	s_add_u32 s62, s76, 0x4000
	v_lshl_add_u64 v[158:159], s[76:77], 0, v[136:137]
	s_addc_u32 s63, s77, 0
	s_add_i32 s59, s82, s3
	global_load_lds_dwordx4 v[158:159], off
	v_lshl_add_u64 v[158:159], s[62:63], 0, v[132:133]
	s_mov_b32 m0, s59
	s_nop 0
	global_load_lds_dwordx4 v[158:159], off
	v_lshl_add_u64 v[158:159], s[62:63], 0, v[136:137]
	s_add_i32 m0, s59, 0x2000
	s_nop 0
	global_load_lds_dwordx4 v[158:159], off
	s_waitcnt vmcnt(6)
	s_waitcnt lgkmcnt(0)
	s_barrier
; #define PG8_STAGE(bufoff, gbase, voff) do { _Pragma("unroll") for (int _i = 0; _i < 2; ++_i) \
;         __builtin_amdgcn_global_load_lds((const unsigned*)((const char*)(gbase) + (voff)[_i]), (PG8_LAS unsigned*)(lds + (bufoff) + ldsw + _i * 8192), 16, 0, 0); } while (0)
; #define PG8_LDA(dst, b, h) do { _Pragma("unroll") for (int m = 0; m < 4; ++m) _Pragma("unroll") for (int k = 0; k < 2; ++k) dst[m][k] = *(const PG8_LAS bf16x8*)(lds + PG8_SA(b, h) + aoff + m * 2048 + k * 1024); } while (0)
; #define PG8_LDB(dst, b, h) do { _Pragma("unroll") for (int n = 0; n < 2; ++n) _Pragma("unroll") for (int k = 0; k < 2; ++k) dst[n][k] = *(const PG8_LAS bf16x8*)(lds + PG8_SB(b, h) + boff + n * 2048 + k * 1024); } while (0)
; #define PG8_MMA(ai, bj, At, Bt) do { __builtin_amdgcn_s_setprio(1); _Pragma("unroll") for (int m = 0; m < 4; ++m) _Pragma("unroll") for (int n = 0; n < 2; ++n) _Pragma("unroll") for (int k = 0; k < 2; ++k) \
;         acc[ai][bj][m][n] = __builtin_amdgcn_mfma_f32_16x16x32_bf16(Bt[n][k], At[m][k], acc[ai][bj][m][n], 0, 0, 0); __builtin_amdgcn_s_setprio(0); } while (0)
; #define PG8_WAIT_V(n) asm volatile("s_waitcnt vmcnt(" #n ")" ::: "memory")
; #define PG8_WAIT_L(n) asm volatile("s_waitcnt lgkmcnt(" #n ")" ::: "memory")
; #define PG8_BAR __builtin_amdgcn_s_barrier()
; #define PG8_SCHED __builtin_amdgcn_sched_barrier(0)
; template <class Epi, class Sched, bool ALIGN_EPI = false, bool SP2 = false>
; __device__ __forceinline__ void gemm_phase(PG8_LAS unsigned char* lds, const Gemm g, const Sched& S, const Epi& E) {
;     ...
;             PG8_LDA(At, 0, 1); PG8_STAGE(PG8_SB(0, 0), b2, voffB); PG8_STAGE(PG8_SB(0, 1), b2 + hstep, voffB); PG8_STAGE(PG8_SA(0, 0), a2, voffA);
;             PG8_WAIT_V(8); PG8_WAIT_L(0); PG8_BAR; PG8_MMA(1, 0, At, B0); PG8_MMA(1, 1, At, B1); PG8_BAR; PG8_SCHED;
;             PG8_LDB(B0, 1, 0); PG8_LDB(B1, 1, 1); PG8_SCHED; PG8_LDA(At, 1, 0); PG8_STAGE(PG8_SA(0, 1), a2 + hstep, voffA);
	s_setprio 1
	s_waitcnt lgkmcnt(0)
	v_mfma_f32_16x16x32_bf16 v[62:65], v[146:149], v[198:201], v[62:65]
	v_mfma_f32_16x16x32_bf16 v[58:61], v[154:157], v[198:201], v[58:61]
	v_mfma_f32_16x16x32_bf16 v[46:49], v[146:149], v[206:209], v[46:49]
	v_mfma_f32_16x16x32_bf16 v[42:45], v[154:157], v[206:209], v[42:45]
	v_mfma_f32_16x16x32_bf16 v[30:33], v[146:149], v[214:217], v[30:33]
	v_mfma_f32_16x16x32_bf16 v[26:29], v[154:157], v[214:217], v[26:29]
	v_mfma_f32_16x16x32_bf16 v[14:17], v[146:149], v[222:225], v[14:17]
	v_mfma_f32_16x16x32_bf16 v[10:13], v[154:157], v[222:225], v[10:13]
	v_mfma_f32_16x16x32_bf16 v[62:65], v[150:153], v[202:205], v[62:65]
	v_mfma_f32_16x16x32_bf16 v[58:61], v[168:171], v[202:205], v[58:61]
	v_mfma_f32_16x16x32_bf16 v[46:49], v[150:153], v[210:213], v[46:49]
	v_mfma_f32_16x16x32_bf16 v[42:45], v[168:171], v[210:213], v[42:45]
	v_mfma_f32_16x16x32_bf16 v[30:33], v[150:153], v[218:221], v[30:33]
	v_mfma_f32_16x16x32_bf16 v[26:29], v[168:171], v[218:221], v[26:29]
	v_mfma_f32_16x16x32_bf16 v[14:17], v[150:153], v[226:229], v[14:17]
	v_mfma_f32_16x16x32_bf16 v[10:13], v[168:171], v[226:229], v[10:13]
	s_setprio 0
	s_setprio 1
	v_mfma_f32_16x16x32_bf16 v[54:57], v[172:175], v[198:201], v[54:57]
	v_mfma_f32_16x16x32_bf16 v[50:53], v[184:187], v[198:201], v[50:53]
	v_mfma_f32_16x16x32_bf16 v[38:41], v[172:175], v[206:209], v[38:41]
	v_mfma_f32_16x16x32_bf16 v[34:37], v[184:187], v[206:209], v[34:37]
	v_mfma_f32_16x16x32_bf16 v[22:25], v[172:175], v[214:217], v[22:25]
	v_mfma_f32_16x16x32_bf16 v[18:21], v[184:187], v[214:217], v[18:21]
	v_mfma_f32_16x16x32_bf16 v[6:9], v[172:175], v[222:225], v[6:9]
	v_mfma_f32_16x16x32_bf16 v[2:5], v[184:187], v[222:225], v[2:5]
	v_mfma_f32_16x16x32_bf16 v[54:57], v[180:183], v[202:205], v[54:57]
	v_mfma_f32_16x16x32_bf16 v[50:53], v[188:191], v[202:205], v[50:53]
	v_mfma_f32_16x16x32_bf16 v[38:41], v[180:183], v[210:213], v[38:41]
	v_mfma_f32_16x16x32_bf16 v[34:37], v[188:191], v[210:213], v[34:37]
	v_mfma_f32_16x16x32_bf16 v[22:25], v[180:183], v[218:221], v[22:25]
	v_mfma_f32_16x16x32_bf16 v[18:21], v[188:191], v[218:221], v[18:21]
	v_mfma_f32_16x16x32_bf16 v[6:9], v[180:183], v[226:229], v[6:9]
	v_mfma_f32_16x16x32_bf16 v[2:5], v[188:191], v[226:229], v[2:5]
	s_setprio 0
	s_barrier
	s_add_i32 s59, 0, 0x18000
	v_add_u32_e32 v158, s59, v160
	s_add_i32 s64, 0, 0x1c000
	ds_read_b128 v[146:149], v158
	ds_read_b128 v[150:153], v158 offset:1024
	ds_read_b128 v[154:157], v158 offset:2048
	ds_read_b128 v[168:171], v158 offset:3072
	v_add_u32_e32 v158, s64, v160
	ds_read_b128 v[172:175], v158
	ds_read_b128 v[180:183], v158 offset:1024
	ds_read_b128 v[184:187], v158 offset:2048
	ds_read_b128 v[188:191], v158 offset:3072
	v_lshl_add_u64 v[158:159], s[78:79], 0, v[130:131]
	s_mov_b32 m0, s15
	s_nop 0
	global_load_lds_dwordx4 v[158:159], off
	v_lshl_add_u64 v[158:159], s[78:79], 0, v[134:135]
	s_mov_b32 m0, s27
	s_nop 0
	global_load_lds_dwordx4 v[158:159], off
	s_add_u32 s62, s78, 0x4000
	s_addc_u32 s63, s79, 0
	s_mov_b32 m0, s28
	v_lshl_add_u64 v[158:159], s[62:63], 0, v[130:131]
	ds_read_b128 v[198:201], v164 offset:32768
	ds_read_b128 v[202:205], v164 offset:33792
	ds_read_b128 v[206:209], v164 offset:34816
	ds_read_b128 v[210:213], v164 offset:35840
	ds_read_b128 v[214:217], v164 offset:36864
	ds_read_b128 v[218:221], v164 offset:37888
	ds_read_b128 v[222:225], v164 offset:38912
	ds_read_b128 v[226:229], v164 offset:39936
	global_load_lds_dwordx4 v[158:159], off
	v_lshl_add_u64 v[158:159], s[62:63], 0, v[134:135]
	s_mov_b32 m0, s29
	s_nop 0
	global_load_lds_dwordx4 v[158:159], off
	s_waitcnt vmcnt(8)
	s_waitcnt lgkmcnt(0)
	s_barrier
; #define PG8_STAGE(bufoff, gbase, voff) do { _Pragma("unroll") for (int _i = 0; _i < 2; ++_i) \
;         __builtin_amdgcn_global_load_lds((const unsigned*)((const char*)(gbase) + (voff)[_i]), (PG8_LAS unsigned*)(lds + (bufoff) + ldsw + _i * 8192), 16, 0, 0); } while (0)
; #define PG8_LDA(dst, b, h) do { _Pragma("unroll") for (int m = 0; m < 4; ++m) _Pragma("unroll") for (int k = 0; k < 2; ++k) dst[m][k] = *(const PG8_LAS bf16x8*)(lds + PG8_SA(b, h) + aoff + m * 2048 + k * 1024); } while (0)
; #define PG8_MMA(ai, bj, At, Bt) do { __builtin_amdgcn_s_setprio(1); _Pragma("unroll") for (int m = 0; m < 4; ++m) _Pragma("unroll") for (int n = 0; n < 2; ++n) _Pragma("unroll") for (int k = 0; k < 2; ++k) \
;         acc[ai][bj][m][n] = __builtin_amdgcn_mfma_f32_16x16x32_bf16(Bt[n][k], At[m][k], acc[ai][bj][m][n], 0, 0, 0); __builtin_amdgcn_s_setprio(0); } while (0)
; #define PG8_WAIT_V(n) asm volatile("s_waitcnt vmcnt(" #n ")" ::: "memory")
; #define PG8_WAIT_L(n) asm volatile("s_waitcnt lgkmcnt(" #n ")" ::: "memory")
; #define PG8_BAR __builtin_amdgcn_s_barrier()
; #define PG8_SCHED __builtin_amdgcn_sched_barrier(0)
; template <class Epi, class Sched, bool ALIGN_EPI = false, bool SP2 = false>
; __device__ __forceinline__ void gemm_phase(PG8_LAS unsigned char* lds, const Gemm g, const Sched& S, const Epi& E) {
;     ...
;             PG8_WAIT_V(8); PG8_WAIT_L(0); PG8_BAR; PG8_MMA(0, 0, At, B0); PG8_MMA(0, 1, At, B1); PG8_BAR; PG8_SCHED;
;             PG8_LDA(At, 1, 1); PG8_STAGE(PG8_SB(1, 0), b3, voffB); PG8_STAGE(PG8_SB(1, 1), b3 + hstep, voffB); PG8_STAGE(PG8_SA(1, 0), a3, voffA);
;             PG8_WAIT_V(8); PG8_WAIT_L(0); PG8_BAR; PG8_MMA(1, 0, At, B0); PG8_MMA(1, 1, At, B1); PG8_BAR; PG8_SCHED;
;     ...
;         if constexpr (ALIGN_EPI) { if (wr == 0) PG8_BAR; }
	s_setprio 1
	s_waitcnt lgkmcnt(0)
	v_mfma_f32_16x16x32_bf16 v[126:129], v[146:149], v[198:201], v[126:129]
	v_mfma_f32_16x16x32_bf16 v[122:125], v[154:157], v[198:201], v[122:125]
	v_mfma_f32_16x16x32_bf16 v[110:113], v[146:149], v[206:209], v[110:113]
	v_mfma_f32_16x16x32_bf16 v[106:109], v[154:157], v[206:209], v[106:109]
	v_mfma_f32_16x16x32_bf16 v[94:97], v[146:149], v[214:217], v[94:97]
	v_mfma_f32_16x16x32_bf16 v[90:93], v[154:157], v[214:217], v[90:93]
	v_mfma_f32_16x16x32_bf16 v[78:81], v[146:149], v[222:225], v[78:81]
	v_mfma_f32_16x16x32_bf16 v[74:77], v[154:157], v[222:225], v[74:77]
	v_mfma_f32_16x16x32_bf16 v[126:129], v[150:153], v[202:205], v[126:129]
	v_mfma_f32_16x16x32_bf16 v[122:125], v[168:171], v[202:205], v[122:125]
	v_mfma_f32_16x16x32_bf16 v[110:113], v[150:153], v[210:213], v[110:113]
	v_mfma_f32_16x16x32_bf16 v[106:109], v[168:171], v[210:213], v[106:109]
	v_mfma_f32_16x16x32_bf16 v[94:97], v[150:153], v[218:221], v[94:97]
	v_mfma_f32_16x16x32_bf16 v[90:93], v[168:171], v[218:221], v[90:93]
	v_mfma_f32_16x16x32_bf16 v[78:81], v[150:153], v[226:229], v[78:81]
	v_mfma_f32_16x16x32_bf16 v[74:77], v[168:171], v[226:229], v[74:77]
	s_setprio 0
	s_setprio 1
	v_mfma_f32_16x16x32_bf16 v[118:121], v[172:175], v[198:201], v[118:121]
	v_mfma_f32_16x16x32_bf16 v[114:117], v[184:187], v[198:201], v[114:117]
	v_mfma_f32_16x16x32_bf16 v[102:105], v[172:175], v[206:209], v[102:105]
	v_mfma_f32_16x16x32_bf16 v[98:101], v[184:187], v[206:209], v[98:101]
	v_mfma_f32_16x16x32_bf16 v[86:89], v[172:175], v[214:217], v[86:89]
	v_mfma_f32_16x16x32_bf16 v[82:85], v[184:187], v[214:217], v[82:85]
	v_mfma_f32_16x16x32_bf16 v[70:73], v[172:175], v[222:225], v[70:73]
	v_mfma_f32_16x16x32_bf16 v[66:69], v[184:187], v[222:225], v[66:69]
	v_mfma_f32_16x16x32_bf16 v[118:121], v[180:183], v[202:205], v[118:121]
	v_mfma_f32_16x16x32_bf16 v[114:117], v[188:191], v[202:205], v[114:117]
	v_mfma_f32_16x16x32_bf16 v[102:105], v[180:183], v[210:213], v[102:105]
	v_mfma_f32_16x16x32_bf16 v[98:101], v[188:191], v[210:213], v[98:101]
	v_mfma_f32_16x16x32_bf16 v[86:89], v[180:183], v[218:221], v[86:89]
	v_mfma_f32_16x16x32_bf16 v[82:85], v[188:191], v[218:221], v[82:85]
	v_mfma_f32_16x16x32_bf16 v[70:73], v[180:183], v[226:229], v[70:73]
	v_mfma_f32_16x16x32_bf16 v[66:69], v[188:191], v[226:229], v[66:69]
	s_setprio 0
	s_barrier
	s_add_u32 s62, s76, 0x8000
	s_addc_u32 s63, s77, 0
	s_add_i32 s59, s59, s3
	v_lshl_add_u64 v[158:159], s[62:63], 0, v[132:133]
	s_mov_b32 m0, s59
	ds_read_b128 v[198:201], v164 offset:49152
	ds_read_b128 v[202:205], v164 offset:50176
	ds_read_b128 v[206:209], v164 offset:51200
	ds_read_b128 v[210:213], v164 offset:52224
	ds_read_b128 v[214:217], v164 offset:53248
	ds_read_b128 v[218:221], v164 offset:54272
	ds_read_b128 v[222:225], v164 offset:55296
	ds_read_b128 v[226:229], v164 offset:56320
	global_load_lds_dwordx4 v[158:159], off
	s_add_i32 m0, s59, 0x2000
	v_lshl_add_u64 v[158:159], s[62:63], 0, v[136:137]
	s_add_u32 s62, s76, 0xc000
	s_addc_u32 s63, s77, 0
	s_add_i32 s59, s64, s3
	global_load_lds_dwordx4 v[158:159], off
	v_lshl_add_u64 v[158:159], s[62:63], 0, v[132:133]
	s_mov_b32 m0, s59
	s_nop 0
	global_load_lds_dwordx4 v[158:159], off
	v_lshl_add_u64 v[158:159], s[62:63], 0, v[136:137]
	s_add_i32 m0, s59, 0x2000
	s_nop 0
	global_load_lds_dwordx4 v[158:159], off
	s_waitcnt vmcnt(6)
	s_waitcnt lgkmcnt(0)
	s_barrier
	s_setprio 1
	s_waitcnt lgkmcnt(0)
	v_mfma_f32_16x16x32_bf16 v[62:65], v[146:149], v[198:201], v[62:65]
	v_mfma_f32_16x16x32_bf16 v[58:61], v[154:157], v[198:201], v[58:61]
	v_mfma_f32_16x16x32_bf16 v[46:49], v[146:149], v[206:209], v[46:49]
	v_mfma_f32_16x16x32_bf16 v[42:45], v[154:157], v[206:209], v[42:45]
	v_mfma_f32_16x16x32_bf16 v[30:33], v[146:149], v[214:217], v[30:33]
	v_mfma_f32_16x16x32_bf16 v[26:29], v[154:157], v[214:217], v[26:29]
	v_mfma_f32_16x16x32_bf16 v[14:17], v[146:149], v[222:225], v[14:17]
	v_mfma_f32_16x16x32_bf16 v[10:13], v[154:157], v[222:225], v[10:13]
	v_mfma_f32_16x16x32_bf16 v[62:65], v[150:153], v[202:205], v[62:65]
	v_mfma_f32_16x16x32_bf16 v[58:61], v[168:171], v[202:205], v[58:61]
	v_mfma_f32_16x16x32_bf16 v[46:49], v[150:153], v[210:213], v[46:49]
	v_mfma_f32_16x16x32_bf16 v[42:45], v[168:171], v[210:213], v[42:45]
	v_mfma_f32_16x16x32_bf16 v[30:33], v[150:153], v[218:221], v[30:33]
	v_mfma_f32_16x16x32_bf16 v[26:29], v[168:171], v[218:221], v[26:29]
	v_mfma_f32_16x16x32_bf16 v[14:17], v[150:153], v[226:229], v[14:17]
	v_mfma_f32_16x16x32_bf16 v[10:13], v[168:171], v[226:229], v[10:13]
	s_setprio 0
	s_setprio 1
	v_mfma_f32_16x16x32_bf16 v[54:57], v[172:175], v[198:201], v[54:57]
	v_mfma_f32_16x16x32_bf16 v[50:53], v[184:187], v[198:201], v[50:53]
	v_mfma_f32_16x16x32_bf16 v[38:41], v[172:175], v[206:209], v[38:41]
	v_mfma_f32_16x16x32_bf16 v[34:37], v[184:187], v[206:209], v[34:37]
	v_mfma_f32_16x16x32_bf16 v[22:25], v[172:175], v[214:217], v[22:25]
	v_mfma_f32_16x16x32_bf16 v[18:21], v[184:187], v[214:217], v[18:21]
	v_mfma_f32_16x16x32_bf16 v[6:9], v[172:175], v[222:225], v[6:9]
	v_mfma_f32_16x16x32_bf16 v[2:5], v[184:187], v[222:225], v[2:5]
	v_mfma_f32_16x16x32_bf16 v[54:57], v[180:183], v[202:205], v[54:57]
	v_mfma_f32_16x16x32_bf16 v[50:53], v[188:191], v[202:205], v[50:53]
	v_mfma_f32_16x16x32_bf16 v[38:41], v[180:183], v[210:213], v[38:41]
	v_mfma_f32_16x16x32_bf16 v[34:37], v[188:191], v[210:213], v[34:37]
	v_mfma_f32_16x16x32_bf16 v[22:25], v[180:183], v[218:221], v[22:25]
	v_mfma_f32_16x16x32_bf16 v[18:21], v[188:191], v[218:221], v[18:21]
	v_mfma_f32_16x16x32_bf16 v[6:9], v[180:183], v[226:229], v[6:9]
	v_mfma_f32_16x16x32_bf16 v[2:5], v[188:191], v[226:229], v[2:5]
	s_setprio 0
	s_barrier
	s_add_i32 s58, s58, 2
	s_add_u32 s72, s72, 0x10000
	s_addc_u32 s73, s73, 0
	s_add_u32 s33, s33, 0x10000
	s_addc_u32 s56, s56, 0
	s_cmp_gt_u32 s58, 61
	s_cbranch_scc0 .LBB0_290
	s_and_b64 vcc, exec, s[12:13]
	s_cbranch_vccz .LBB0_293
	s_barrier

; #define PG8_STAGE(bufoff, gbase, voff) do { _Pragma("unroll") for (int _i = 0; _i < 2; ++_i) \
;         __builtin_amdgcn_global_load_lds((const unsigned*)((const char*)(gbase) + (voff)[_i]), (PG8_LAS unsigned*)(lds + (bufoff) + ldsw + _i * 8192), 16, 0, 0); } while (0)
; #define PG8_LDA(dst, b, h) do { _Pragma("unroll") for (int m = 0; m < 4; ++m) _Pragma("unroll") for (int k = 0; k < 2; ++k) dst[m][k] = *(const PG8_LAS bf16x8*)(lds + PG8_SA(b, h) + aoff + m * 2048 + k * 1024); } while (0)
; #define PG8_LDB(dst, b, h) do { _Pragma("unroll") for (int n = 0; n < 2; ++n) _Pragma("unroll") for (int k = 0; k < 2; ++k) dst[n][k] = *(const PG8_LAS bf16x8*)(lds + PG8_SB(b, h) + boff + n * 2048 + k * 1024); } while (0)
; #define PG8_MMA(ai, bj, At, Bt) do { __builtin_amdgcn_s_setprio(1); _Pragma("unroll") for (int m = 0; m < 4; ++m) _Pragma("unroll") for (int n = 0; n < 2; ++n) _Pragma("unroll") for (int k = 0; k < 2; ++k) \
;         acc[ai][bj][m][n] = __builtin_amdgcn_mfma_f32_16x16x32_bf16(Bt[n][k], At[m][k], acc[ai][bj][m][n], 0, 0, 0); __builtin_amdgcn_s_setprio(0); } while (0)
; #define PG8_WAIT_V(n) asm volatile("s_waitcnt vmcnt(" #n ")" ::: "memory")
; #define PG8_WAIT_L(n) asm volatile("s_waitcnt lgkmcnt(" #n ")" ::: "memory")
; #define PG8_BAR __builtin_amdgcn_s_barrier()
; #define PG8_SCHED __builtin_amdgcn_sched_barrier(0)
; template <class Epi, class Sched, bool ALIGN_EPI = false, bool SP2 = false>
; __device__ __forceinline__ void gemm_phase(PG8_LAS unsigned char* lds, const Gemm g, const Sched& S, const Epi& E) {
;     ...
;             const bool last = (t == nt - 2);
;             const char* a1 = cA + (size_t)(t + 1) * kstep;
;             const char* a2 = last ? nA : cA + (size_t)(t + 2) * kstep; const char* b2 = last ? nB : cB + (size_t)(t + 2) * kstep;
;             const char* a3 = a2 + kstep; const char* b3 = b2 + kstep;
;             if (last && has_next) S.a_ready(nxt);
;             if constexpr (SP2) {
;             PG8_LDB(B0, 0, 0); PG8_LDB(B1, 0, 1); PG8_SCHED; PG8_LDA(At, 0, 0); PG8_STAGE(PG8_SA(1, 1), a1 + hstep, voffA);
;             PG8_WAIT_V(8); PG8_WAIT_L(0); PG8_BAR; PG8_MMA(0, 0, At, B0); PG8_MMA(0, 1, At, B1); PG8_BAR; PG8_SCHED;
;             PG8_LDA(At, 0, 1); PG8_STAGE(PG8_SB(0, 0), b2, voffB); PG8_STAGE(PG8_SB(0, 1), b2 + hstep, voffB); PG8_STAGE(PG8_SA(0, 0), a2, voffA);
.LBB0_757:
	ds_read_b128 v[154:157], v149
	ds_read_b128 v[158:161], v149 offset:1024
	ds_read_b128 v[162:165], v149 offset:2048
	ds_read_b128 v[166:169], v149 offset:3072
	ds_read_b128 v[170:173], v150
	ds_read_b128 v[174:177], v150 offset:1024
	ds_read_b128 v[180:183], v150 offset:2048
	ds_read_b128 v[184:187], v150 offset:3072
	s_add_u32 s46, s44, 0x4000
	s_addc_u32 s47, s45, 0
	s_cmp_eq_u32 s70, 60
	s_cselect_b32 s50, s39, s46
	s_cselect_b32 s51, s17, s47
	s_cselect_b32 s48, s41, s68
	s_cselect_b32 s49, s15, s69
	s_sub_u32 s46, s44, 0x4000
	s_subb_u32 s47, s45, 0
	v_lshl_add_u64 v[146:147], s[46:47], 0, v[130:131]
	s_mov_b32 m0, s57
	s_nop 0
	global_load_lds_dwordx4 v[146:147], off
	v_lshl_add_u64 v[146:147], s[46:47], 0, v[134:135]
	s_mov_b32 m0, s58
	s_nop 0
	global_load_lds_dwordx4 v[146:147], off
	v_lshl_add_u64 v[146:147], s[44:45], 0, v[138:139]
	s_add_i32 m0, s26, 0xc000
	ds_read_b128 v[188:191], v151
	ds_read_b128 v[198:201], v151 offset:1024
	ds_read_b128 v[202:205], v151 offset:2048
	ds_read_b128 v[206:209], v151 offset:3072
	ds_read_b128 v[210:213], v151 offset:4096
	ds_read_b128 v[214:217], v151 offset:5120
	ds_read_b128 v[218:221], v151 offset:6144
	ds_read_b128 v[222:225], v151 offset:7168
	global_load_lds_dwordx4 v[146:147], off
	v_lshl_add_u64 v[146:147], s[44:45], 0, v[140:141]
	s_add_i32 m0, s26, 0xe000
	s_nop 0
	global_load_lds_dwordx4 v[146:147], off
	s_waitcnt vmcnt(8)
	s_waitcnt lgkmcnt(0)
	s_barrier
	s_setprio 1
	s_waitcnt lgkmcnt(0)
	v_mfma_f32_16x16x32_bf16 v[126:129], v[154:157], v[188:191], v[126:129]
	v_mfma_f32_16x16x32_bf16 v[122:125], v[162:165], v[188:191], v[122:125]
	v_mfma_f32_16x16x32_bf16 v[110:113], v[154:157], v[202:205], v[110:113]
	v_mfma_f32_16x16x32_bf16 v[106:109], v[162:165], v[202:205], v[106:109]
	v_mfma_f32_16x16x32_bf16 v[94:97], v[154:157], v[210:213], v[94:97]
	v_mfma_f32_16x16x32_bf16 v[90:93], v[162:165], v[210:213], v[90:93]
	v_mfma_f32_16x16x32_bf16 v[78:81], v[154:157], v[218:221], v[78:81]
	v_mfma_f32_16x16x32_bf16 v[74:77], v[162:165], v[218:221], v[74:77]
	v_mfma_f32_16x16x32_bf16 v[126:129], v[158:161], v[198:201], v[126:129]
	v_mfma_f32_16x16x32_bf16 v[122:125], v[166:169], v[198:201], v[122:125]
	v_mfma_f32_16x16x32_bf16 v[110:113], v[158:161], v[206:209], v[110:113]
	v_mfma_f32_16x16x32_bf16 v[106:109], v[166:169], v[206:209], v[106:109]
	v_mfma_f32_16x16x32_bf16 v[94:97], v[158:161], v[214:217], v[94:97]
	v_mfma_f32_16x16x32_bf16 v[90:93], v[166:169], v[214:217], v[90:93]
	v_mfma_f32_16x16x32_bf16 v[78:81], v[158:161], v[222:225], v[78:81]
	v_mfma_f32_16x16x32_bf16 v[74:77], v[166:169], v[222:225], v[74:77]
	s_setprio 0
	s_setprio 1
	v_mfma_f32_16x16x32_bf16 v[118:121], v[170:173], v[188:191], v[118:121]
	v_mfma_f32_16x16x32_bf16 v[114:117], v[180:183], v[188:191], v[114:117]
	v_mfma_f32_16x16x32_bf16 v[102:105], v[170:173], v[202:205], v[102:105]
	v_mfma_f32_16x16x32_bf16 v[98:101], v[180:183], v[202:205], v[98:101]
	v_mfma_f32_16x16x32_bf16 v[86:89], v[170:173], v[210:213], v[86:89]
	v_mfma_f32_16x16x32_bf16 v[82:85], v[180:183], v[210:213], v[82:85]
	v_mfma_f32_16x16x32_bf16 v[70:73], v[170:173], v[218:221], v[70:73]
	v_mfma_f32_16x16x32_bf16 v[66:69], v[180:183], v[218:221], v[66:69]
	v_mfma_f32_16x16x32_bf16 v[118:121], v[174:177], v[198:201], v[118:121]
	v_mfma_f32_16x16x32_bf16 v[114:117], v[184:187], v[198:201], v[114:117]
	v_mfma_f32_16x16x32_bf16 v[102:105], v[174:177], v[206:209], v[102:105]
	v_mfma_f32_16x16x32_bf16 v[98:101], v[184:187], v[206:209], v[98:101]
	v_mfma_f32_16x16x32_bf16 v[86:89], v[174:177], v[214:217], v[86:89]
	v_mfma_f32_16x16x32_bf16 v[82:85], v[184:187], v[214:217], v[82:85]
	v_mfma_f32_16x16x32_bf16 v[70:73], v[174:177], v[222:225], v[70:73]
	v_mfma_f32_16x16x32_bf16 v[66:69], v[184:187], v[222:225], v[66:69]
	s_setprio 0
	s_barrier
	s_add_i32 s71, s59, s3
	v_lshl_add_u64 v[146:147], s[48:49], 0, v[132:133]
	s_mov_b32 m0, s71
	ds_read_b128 v[188:191], v151 offset:16384
	ds_read_b128 v[198:201], v151 offset:17408
	ds_read_b128 v[202:205], v151 offset:18432
	ds_read_b128 v[206:209], v151 offset:19456
	ds_read_b128 v[210:213], v151 offset:20480
	ds_read_b128 v[214:217], v151 offset:21504
	ds_read_b128 v[218:221], v151 offset:22528
	ds_read_b128 v[222:225], v151 offset:23552
	global_load_lds_dwordx4 v[146:147], off
	s_add_i32 m0, s71, 0x2000
	s_add_u32 s72, s48, 0x4000
	v_lshl_add_u64 v[146:147], s[48:49], 0, v[136:137]
	s_addc_u32 s73, s49, 0
	s_add_i32 s71, s61, s3
	global_load_lds_dwordx4 v[146:147], off
	v_lshl_add_u64 v[146:147], s[72:73], 0, v[132:133]
	s_mov_b32 m0, s71
	s_nop 0
	global_load_lds_dwordx4 v[146:147], off
	v_lshl_add_u64 v[146:147], s[72:73], 0, v[136:137]
	s_add_i32 m0, s71, 0x2000
	s_nop 0
	global_load_lds_dwordx4 v[146:147], off
	s_waitcnt vmcnt(6)
	s_waitcnt lgkmcnt(0)
	s_barrier
; #define PG8_STAGE(bufoff, gbase, voff) do { _Pragma("unroll") for (int _i = 0; _i < 2; ++_i) \
;         __builtin_amdgcn_global_load_lds((const unsigned*)((const char*)(gbase) + (voff)[_i]), (PG8_LAS unsigned*)(lds + (bufoff) + ldsw + _i * 8192), 16, 0, 0); } while (0)
; #define PG8_LDA(dst, b, h) do { _Pragma("unroll") for (int m = 0; m < 4; ++m) _Pragma("unroll") for (int k = 0; k < 2; ++k) dst[m][k] = *(const PG8_LAS bf16x8*)(lds + PG8_SA(b, h) + aoff + m * 2048 + k * 1024); } while (0)
; #define PG8_LDB(dst, b, h) do { _Pragma("unroll") for (int n = 0; n < 2; ++n) _Pragma("unroll") for (int k = 0; k < 2; ++k) dst[n][k] = *(const PG8_LAS bf16x8*)(lds + PG8_SB(b, h) + boff + n * 2048 + k * 1024); } while (0)
; #define PG8_MMA(ai, bj, At, Bt) do { __builtin_amdgcn_s_setprio(1); _Pragma("unroll") for (int m = 0; m < 4; ++m) _Pragma("unroll") for (int n = 0; n < 2; ++n) _Pragma("unroll") for (int k = 0; k < 2; ++k) \
;         acc[ai][bj][m][n] = __builtin_amdgcn_mfma_f32_16x16x32_bf16(Bt[n][k], At[m][k], acc[ai][bj][m][n], 0, 0, 0); __builtin_amdgcn_s_setprio(0); } while (0)
; #define PG8_WAIT_V(n) asm volatile("s_waitcnt vmcnt(" #n ")" ::: "memory")
; #define PG8_WAIT_L(n) asm volatile("s_waitcnt lgkmcnt(" #n ")" ::: "memory")
; #define PG8_BAR __builtin_amdgcn_s_barrier()
; #define PG8_SCHED __builtin_amdgcn_sched_barrier(0)
; template <class Epi, class Sched, bool ALIGN_EPI = false, bool SP2 = false>
; __device__ __forceinline__ void gemm_phase(PG8_LAS unsigned char* lds, const Gemm g, const Sched& S, const Epi& E) {
;     ...
;             PG8_LDA(At, 0, 1); PG8_STAGE(PG8_SB(0, 0), b2, voffB); PG8_STAGE(PG8_SB(0, 1), b2 + hstep, voffB); PG8_STAGE(PG8_SA(0, 0), a2, voffA);
;             PG8_WAIT_V(8); PG8_WAIT_L(0); PG8_BAR; PG8_MMA(1, 0, At, B0); PG8_MMA(1, 1, At, B1); PG8_BAR; PG8_SCHED;
;             PG8_LDB(B0, 1, 0); PG8_LDB(B1, 1, 1); PG8_SCHED; PG8_LDA(At, 1, 0); PG8_STAGE(PG8_SA(0, 1), a2 + hstep, voffA);
	s_setprio 1
	s_waitcnt lgkmcnt(0)
	v_mfma_f32_16x16x32_bf16 v[62:65], v[154:157], v[188:191], v[62:65]
	v_mfma_f32_16x16x32_bf16 v[58:61], v[162:165], v[188:191], v[58:61]
	v_mfma_f32_16x16x32_bf16 v[46:49], v[154:157], v[202:205], v[46:49]
	v_mfma_f32_16x16x32_bf16 v[42:45], v[162:165], v[202:205], v[42:45]
	v_mfma_f32_16x16x32_bf16 v[30:33], v[154:157], v[210:213], v[30:33]
	v_mfma_f32_16x16x32_bf16 v[26:29], v[162:165], v[210:213], v[26:29]
	v_mfma_f32_16x16x32_bf16 v[14:17], v[154:157], v[218:221], v[14:17]
	v_mfma_f32_16x16x32_bf16 v[10:13], v[162:165], v[218:221], v[10:13]
	v_mfma_f32_16x16x32_bf16 v[62:65], v[158:161], v[198:201], v[62:65]
	v_mfma_f32_16x16x32_bf16 v[58:61], v[166:169], v[198:201], v[58:61]
	v_mfma_f32_16x16x32_bf16 v[46:49], v[158:161], v[206:209], v[46:49]
	v_mfma_f32_16x16x32_bf16 v[42:45], v[166:169], v[206:209], v[42:45]
	v_mfma_f32_16x16x32_bf16 v[30:33], v[158:161], v[214:217], v[30:33]
	v_mfma_f32_16x16x32_bf16 v[26:29], v[166:169], v[214:217], v[26:29]
	v_mfma_f32_16x16x32_bf16 v[14:17], v[158:161], v[222:225], v[14:17]
	v_mfma_f32_16x16x32_bf16 v[10:13], v[166:169], v[222:225], v[10:13]
	s_setprio 0
	s_setprio 1
	v_mfma_f32_16x16x32_bf16 v[54:57], v[170:173], v[188:191], v[54:57]
	v_mfma_f32_16x16x32_bf16 v[50:53], v[180:183], v[188:191], v[50:53]
	v_mfma_f32_16x16x32_bf16 v[38:41], v[170:173], v[202:205], v[38:41]
	v_mfma_f32_16x16x32_bf16 v[34:37], v[180:183], v[202:205], v[34:37]
	v_mfma_f32_16x16x32_bf16 v[22:25], v[170:173], v[210:213], v[22:25]
	v_mfma_f32_16x16x32_bf16 v[18:21], v[180:183], v[210:213], v[18:21]
	v_mfma_f32_16x16x32_bf16 v[6:9], v[170:173], v[218:221], v[6:9]
	v_mfma_f32_16x16x32_bf16 v[2:5], v[180:183], v[218:221], v[2:5]
	v_mfma_f32_16x16x32_bf16 v[54:57], v[174:177], v[198:201], v[54:57]
	v_mfma_f32_16x16x32_bf16 v[50:53], v[184:187], v[198:201], v[50:53]
	v_mfma_f32_16x16x32_bf16 v[38:41], v[174:177], v[206:209], v[38:41]
	v_mfma_f32_16x16x32_bf16 v[34:37], v[184:187], v[206:209], v[34:37]
	v_mfma_f32_16x16x32_bf16 v[22:25], v[174:177], v[214:217], v[22:25]
	v_mfma_f32_16x16x32_bf16 v[18:21], v[184:187], v[214:217], v[18:21]
	v_mfma_f32_16x16x32_bf16 v[6:9], v[174:177], v[222:225], v[6:9]
	v_mfma_f32_16x16x32_bf16 v[2:5], v[184:187], v[222:225], v[2:5]
	s_setprio 0
	s_barrier
	s_add_i32 s71, 0, 0x18000
	v_add_u32_e32 v146, s71, v1
	s_add_i32 s72, 0, 0x1c000
	ds_read_b128 v[154:157], v146
	ds_read_b128 v[158:161], v146 offset:1024
	ds_read_b128 v[162:165], v146 offset:2048
	ds_read_b128 v[166:169], v146 offset:3072
	v_add_u32_e32 v146, s72, v1
	ds_read_b128 v[170:173], v146
	ds_read_b128 v[174:177], v146 offset:1024
	ds_read_b128 v[180:183], v146 offset:2048
	ds_read_b128 v[184:187], v146 offset:3072
	v_lshl_add_u64 v[146:147], s[50:51], 0, v[130:131]
	s_mov_b32 m0, s26
	s_nop 0
	global_load_lds_dwordx4 v[146:147], off
	v_lshl_add_u64 v[146:147], s[50:51], 0, v[134:135]
	s_mov_b32 m0, s27
	s_nop 0
	global_load_lds_dwordx4 v[146:147], off
	s_add_u32 s50, s50, 0x4000
	s_addc_u32 s51, s51, 0
	s_mov_b32 m0, s28
	v_lshl_add_u64 v[146:147], s[50:51], 0, v[130:131]
	ds_read_b128 v[188:191], v151 offset:32768
	ds_read_b128 v[198:201], v151 offset:33792
	ds_read_b128 v[202:205], v151 offset:34816
	ds_read_b128 v[206:209], v151 offset:35840
	ds_read_b128 v[210:213], v151 offset:36864
	ds_read_b128 v[214:217], v151 offset:37888
	ds_read_b128 v[218:221], v151 offset:38912
	ds_read_b128 v[222:225], v151 offset:39936
	global_load_lds_dwordx4 v[146:147], off
	v_lshl_add_u64 v[146:147], s[50:51], 0, v[134:135]
	s_mov_b32 m0, s29
	s_nop 0
	global_load_lds_dwordx4 v[146:147], off
	s_waitcnt vmcnt(8)
	s_waitcnt lgkmcnt(0)
	s_barrier
; #define PG8_STAGE(bufoff, gbase, voff) do { _Pragma("unroll") for (int _i = 0; _i < 2; ++_i) \
;         __builtin_amdgcn_global_load_lds((const unsigned*)((const char*)(gbase) + (voff)[_i]), (PG8_LAS unsigned*)(lds + (bufoff) + ldsw + _i * 8192), 16, 0, 0); } while (0)
; #define PG8_LDA(dst, b, h) do { _Pragma("unroll") for (int m = 0; m < 4; ++m) _Pragma("unroll") for (int k = 0; k < 2; ++k) dst[m][k] = *(const PG8_LAS bf16x8*)(lds + PG8_SA(b, h) + aoff + m * 2048 + k * 1024); } while (0)
; #define PG8_MMA(ai, bj, At, Bt) do { __builtin_amdgcn_s_setprio(1); _Pragma("unroll") for (int m = 0; m < 4; ++m) _Pragma("unroll") for (int n = 0; n < 2; ++n) _Pragma("unroll") for (int k = 0; k < 2; ++k) \
;         acc[ai][bj][m][n] = __builtin_amdgcn_mfma_f32_16x16x32_bf16(Bt[n][k], At[m][k], acc[ai][bj][m][n], 0, 0, 0); __builtin_amdgcn_s_setprio(0); } while (0)
; #define PG8_WAIT_V(n) asm volatile("s_waitcnt vmcnt(" #n ")" ::: "memory")
; #define PG8_WAIT_L(n) asm volatile("s_waitcnt lgkmcnt(" #n ")" ::: "memory")
; #define PG8_BAR __builtin_amdgcn_s_barrier()
; #define PG8_SCHED __builtin_amdgcn_sched_barrier(0)
; template <class Epi, class Sched, bool ALIGN_EPI = false, bool SP2 = false>
; __device__ __forceinline__ void gemm_phase(PG8_LAS unsigned char* lds, const Gemm g, const Sched& S, const Epi& E) {
;     ...
;             PG8_WAIT_V(8); PG8_WAIT_L(0); PG8_BAR; PG8_MMA(0, 0, At, B0); PG8_MMA(0, 1, At, B1); PG8_BAR; PG8_SCHED;
;             PG8_LDA(At, 1, 1); PG8_STAGE(PG8_SB(1, 0), b3, voffB); PG8_STAGE(PG8_SB(1, 1), b3 + hstep, voffB); PG8_STAGE(PG8_SA(1, 0), a3, voffA);
;             PG8_WAIT_V(8); PG8_WAIT_L(0); PG8_BAR; PG8_MMA(1, 0, At, B0); PG8_MMA(1, 1, At, B1); PG8_BAR; PG8_SCHED;
;     ...
;         if constexpr (ALIGN_EPI) { if (wr == 0) PG8_BAR; }
	s_setprio 1
	s_waitcnt lgkmcnt(0)
	v_mfma_f32_16x16x32_bf16 v[126:129], v[154:157], v[188:191], v[126:129]
	v_mfma_f32_16x16x32_bf16 v[122:125], v[162:165], v[188:191], v[122:125]
	v_mfma_f32_16x16x32_bf16 v[110:113], v[154:157], v[202:205], v[110:113]
	v_mfma_f32_16x16x32_bf16 v[106:109], v[162:165], v[202:205], v[106:109]
	v_mfma_f32_16x16x32_bf16 v[94:97], v[154:157], v[210:213], v[94:97]
	v_mfma_f32_16x16x32_bf16 v[90:93], v[162:165], v[210:213], v[90:93]
	v_mfma_f32_16x16x32_bf16 v[78:81], v[154:157], v[218:221], v[78:81]
	v_mfma_f32_16x16x32_bf16 v[74:77], v[162:165], v[218:221], v[74:77]
	v_mfma_f32_16x16x32_bf16 v[126:129], v[158:161], v[198:201], v[126:129]
	v_mfma_f32_16x16x32_bf16 v[122:125], v[166:169], v[198:201], v[122:125]
	v_mfma_f32_16x16x32_bf16 v[110:113], v[158:161], v[206:209], v[110:113]
	v_mfma_f32_16x16x32_bf16 v[106:109], v[166:169], v[206:209], v[106:109]
	v_mfma_f32_16x16x32_bf16 v[94:97], v[158:161], v[214:217], v[94:97]
	v_mfma_f32_16x16x32_bf16 v[90:93], v[166:169], v[214:217], v[90:93]
	v_mfma_f32_16x16x32_bf16 v[78:81], v[158:161], v[222:225], v[78:81]
	v_mfma_f32_16x16x32_bf16 v[74:77], v[166:169], v[222:225], v[74:77]
	s_setprio 0
	s_setprio 1
	v_mfma_f32_16x16x32_bf16 v[118:121], v[170:173], v[188:191], v[118:121]
	v_mfma_f32_16x16x32_bf16 v[114:117], v[180:183], v[188:191], v[114:117]
	v_mfma_f32_16x16x32_bf16 v[102:105], v[170:173], v[202:205], v[102:105]
	v_mfma_f32_16x16x32_bf16 v[98:101], v[180:183], v[202:205], v[98:101]
	v_mfma_f32_16x16x32_bf16 v[86:89], v[170:173], v[210:213], v[86:89]
	v_mfma_f32_16x16x32_bf16 v[82:85], v[180:183], v[210:213], v[82:85]
	v_mfma_f32_16x16x32_bf16 v[70:73], v[170:173], v[218:221], v[70:73]
	v_mfma_f32_16x16x32_bf16 v[66:69], v[180:183], v[218:221], v[66:69]
	v_mfma_f32_16x16x32_bf16 v[118:121], v[174:177], v[198:201], v[118:121]
	v_mfma_f32_16x16x32_bf16 v[114:117], v[184:187], v[198:201], v[114:117]
	v_mfma_f32_16x16x32_bf16 v[102:105], v[174:177], v[206:209], v[102:105]
	v_mfma_f32_16x16x32_bf16 v[98:101], v[184:187], v[206:209], v[98:101]
	v_mfma_f32_16x16x32_bf16 v[86:89], v[174:177], v[214:217], v[86:89]
	v_mfma_f32_16x16x32_bf16 v[82:85], v[184:187], v[214:217], v[82:85]
	v_mfma_f32_16x16x32_bf16 v[70:73], v[174:177], v[222:225], v[70:73]
	v_mfma_f32_16x16x32_bf16 v[66:69], v[184:187], v[222:225], v[66:69]
	s_setprio 0
	s_barrier
	s_add_u32 s50, s48, 0x8000
	s_addc_u32 s51, s49, 0
	s_add_i32 s71, s71, s3
	v_lshl_add_u64 v[146:147], s[50:51], 0, v[132:133]
	s_mov_b32 m0, s71
	ds_read_b128 v[188:191], v151 offset:49152
	ds_read_b128 v[198:201], v151 offset:50176
	ds_read_b128 v[202:205], v151 offset:51200
	ds_read_b128 v[206:209], v151 offset:52224
	ds_read_b128 v[210:213], v151 offset:53248
	ds_read_b128 v[214:217], v151 offset:54272
	ds_read_b128 v[218:221], v151 offset:55296
	ds_read_b128 v[222:225], v151 offset:56320
	global_load_lds_dwordx4 v[146:147], off
	s_add_i32 m0, s71, 0x2000
	s_add_u32 s48, s48, 0xc000
	v_lshl_add_u64 v[146:147], s[50:51], 0, v[136:137]
	s_addc_u32 s49, s49, 0
	s_add_i32 s50, s72, s3
	global_load_lds_dwordx4 v[146:147], off
	v_lshl_add_u64 v[146:147], s[48:49], 0, v[132:133]
	s_mov_b32 m0, s50
	s_nop 0
	global_load_lds_dwordx4 v[146:147], off
	v_lshl_add_u64 v[146:147], s[48:49], 0, v[136:137]
	s_add_i32 m0, s50, 0x2000
	s_nop 0
	global_load_lds_dwordx4 v[146:147], off
	s_waitcnt vmcnt(6)
	s_waitcnt lgkmcnt(0)
	s_barrier
	s_setprio 1
	s_waitcnt lgkmcnt(0)
	v_mfma_f32_16x16x32_bf16 v[62:65], v[154:157], v[188:191], v[62:65]
	v_mfma_f32_16x16x32_bf16 v[58:61], v[162:165], v[188:191], v[58:61]
	v_mfma_f32_16x16x32_bf16 v[46:49], v[154:157], v[202:205], v[46:49]
	v_mfma_f32_16x16x32_bf16 v[42:45], v[162:165], v[202:205], v[42:45]
	v_mfma_f32_16x16x32_bf16 v[30:33], v[154:157], v[210:213], v[30:33]
	v_mfma_f32_16x16x32_bf16 v[26:29], v[162:165], v[210:213], v[26:29]
	v_mfma_f32_16x16x32_bf16 v[14:17], v[154:157], v[218:221], v[14:17]
	v_mfma_f32_16x16x32_bf16 v[10:13], v[162:165], v[218:221], v[10:13]
	v_mfma_f32_16x16x32_bf16 v[62:65], v[158:161], v[198:201], v[62:65]
	v_mfma_f32_16x16x32_bf16 v[58:61], v[166:169], v[198:201], v[58:61]
	v_mfma_f32_16x16x32_bf16 v[46:49], v[158:161], v[206:209], v[46:49]
	v_mfma_f32_16x16x32_bf16 v[42:45], v[166:169], v[206:209], v[42:45]
	v_mfma_f32_16x16x32_bf16 v[30:33], v[158:161], v[214:217], v[30:33]
	v_mfma_f32_16x16x32_bf16 v[26:29], v[166:169], v[214:217], v[26:29]
	v_mfma_f32_16x16x32_bf16 v[14:17], v[158:161], v[222:225], v[14:17]
	v_mfma_f32_16x16x32_bf16 v[10:13], v[166:169], v[222:225], v[10:13]
	s_setprio 0
	s_setprio 1
	v_mfma_f32_16x16x32_bf16 v[54:57], v[170:173], v[188:191], v[54:57]
	v_mfma_f32_16x16x32_bf16 v[50:53], v[180:183], v[188:191], v[50:53]
	v_mfma_f32_16x16x32_bf16 v[38:41], v[170:173], v[202:205], v[38:41]
	v_mfma_f32_16x16x32_bf16 v[34:37], v[180:183], v[202:205], v[34:37]
	v_mfma_f32_16x16x32_bf16 v[22:25], v[170:173], v[210:213], v[22:25]
	v_mfma_f32_16x16x32_bf16 v[18:21], v[180:183], v[210:213], v[18:21]
	v_mfma_f32_16x16x32_bf16 v[6:9], v[170:173], v[218:221], v[6:9]
	v_mfma_f32_16x16x32_bf16 v[2:5], v[180:183], v[218:221], v[2:5]
	v_mfma_f32_16x16x32_bf16 v[54:57], v[174:177], v[198:201], v[54:57]
	v_mfma_f32_16x16x32_bf16 v[50:53], v[184:187], v[198:201], v[50:53]
	v_mfma_f32_16x16x32_bf16 v[38:41], v[174:177], v[206:209], v[38:41]
	v_mfma_f32_16x16x32_bf16 v[34:37], v[184:187], v[206:209], v[34:37]
	v_mfma_f32_16x16x32_bf16 v[22:25], v[174:177], v[214:217], v[22:25]
	v_mfma_f32_16x16x32_bf16 v[18:21], v[184:187], v[214:217], v[18:21]
	v_mfma_f32_16x16x32_bf16 v[6:9], v[174:177], v[222:225], v[6:9]
	v_mfma_f32_16x16x32_bf16 v[2:5], v[184:187], v[222:225], v[2:5]
	s_setprio 0
	s_barrier
	s_add_i32 s70, s70, 2
	s_add_u32 s44, s44, 0x10000
	s_addc_u32 s45, s45, 0
	s_add_u32 s68, s68, 0x10000
	s_addc_u32 s69, s69, 0
	s_cmp_gt_u32 s70, 61
	s_cbranch_scc0 .LBB0_757
	s_and_b64 vcc, exec, s[12:13]
	s_cbranch_vccz .LBB0_760
	s_barrier

; #define PG8_STAGE(bufoff, gbase, voff) do { _Pragma("unroll") for (int _i = 0; _i < 2; ++_i) \
;         __builtin_amdgcn_global_load_lds((const unsigned*)((const char*)(gbase) + (voff)[_i]), (PG8_LAS unsigned*)(lds + (bufoff) + ldsw + _i * 8192), 16, 0, 0); } while (0)
; #define PG8_LDA(dst, b, h) do { _Pragma("unroll") for (int m = 0; m < 4; ++m) _Pragma("unroll") for (int k = 0; k < 2; ++k) dst[m][k] = *(const PG8_LAS bf16x8*)(lds + PG8_SA(b, h) + aoff + m * 2048 + k * 1024); } while (0)
; #define PG8_LDB(dst, b, h) do { _Pragma("unroll") for (int n = 0; n < 2; ++n) _Pragma("unroll") for (int k = 0; k < 2; ++k) dst[n][k] = *(const PG8_LAS bf16x8*)(lds + PG8_SB(b, h) + boff + n * 2048 + k * 1024); } while (0)
; #define PG8_MMA(ai, bj, At, Bt) do { __builtin_amdgcn_s_setprio(1); _Pragma("unroll") for (int m = 0; m < 4; ++m) _Pragma("unroll") for (int n = 0; n < 2; ++n) _Pragma("unroll") for (int k = 0; k < 2; ++k) \
;         acc[ai][bj][m][n] = __builtin_amdgcn_mfma_f32_16x16x32_bf16(Bt[n][k], At[m][k], acc[ai][bj][m][n], 0, 0, 0); __builtin_amdgcn_s_setprio(0); } while (0)
; #define PG8_WAIT_V(n) asm volatile("s_waitcnt vmcnt(" #n ")" ::: "memory")
; #define PG8_WAIT_L(n) asm volatile("s_waitcnt lgkmcnt(" #n ")" ::: "memory")
; #define PG8_BAR __builtin_amdgcn_s_barrier()
; #define PG8_SCHED __builtin_amdgcn_sched_barrier(0)
; template <class Epi, class Sched, bool ALIGN_EPI = false, bool SP2 = false>
; __device__ __forceinline__ void gemm_phase(PG8_LAS unsigned char* lds, const Gemm g, const Sched& S, const Epi& E) {
;     ...
;             const bool last = (t == nt - 2);
;             const char* a1 = cA + (size_t)(t + 1) * kstep;
;             const char* a2 = last ? nA : cA + (size_t)(t + 2) * kstep; const char* b2 = last ? nB : cB + (size_t)(t + 2) * kstep;
;             const char* a3 = a2 + kstep; const char* b3 = b2 + kstep;
;             if (last && has_next) S.a_ready(nxt);
;             if constexpr (SP2) {
;             PG8_LDB(B0, 0, 0); PG8_LDB(B1, 0, 1); PG8_SCHED; PG8_LDA(At, 0, 0); PG8_STAGE(PG8_SA(1, 1), a1 + hstep, voffA);
;             PG8_WAIT_V(8); PG8_WAIT_L(0); PG8_BAR; PG8_MMA(0, 0, At, B0); PG8_MMA(0, 1, At, B1); PG8_BAR; PG8_SCHED;
;             PG8_LDA(At, 0, 1); PG8_STAGE(PG8_SB(0, 0), b2, voffB); PG8_STAGE(PG8_SB(0, 1), b2 + hstep, voffB); PG8_STAGE(PG8_SA(0, 0), a2, voffA);
.LBB0_840:
	ds_read_b128 v[148:151], v153
	ds_read_b128 v[158:161], v153 offset:1024
	ds_read_b128 v[162:165], v153 offset:2048
	ds_read_b128 v[166:169], v153 offset:3072
	ds_read_b128 v[170:173], v154
	ds_read_b128 v[174:177], v154 offset:1024
	ds_read_b128 v[180:183], v154 offset:2048
	ds_read_b128 v[184:187], v154 offset:3072
	s_add_u32 s42, s40, 0x4000
	s_addc_u32 s43, s41, 0
	s_cmp_eq_u32 s69, 60
	s_cselect_b32 s46, s65, s42
	s_cselect_b32 s47, s23, s43
	s_cselect_b32 s44, s66, s67
	s_cselect_b32 s45, s17, s68
	s_sub_u32 s42, s40, 0x4000
	s_subb_u32 s43, s41, 0
	v_lshl_add_u64 v[226:227], s[42:43], 0, v[130:131]
	s_mov_b32 m0, s50
	s_nop 0
	global_load_lds_dwordx4 v[226:227], off
	v_lshl_add_u64 v[226:227], s[42:43], 0, v[134:135]
	s_mov_b32 m0, s51
	s_nop 0
	global_load_lds_dwordx4 v[226:227], off
	v_lshl_add_u64 v[226:227], s[40:41], 0, v[140:141]
	s_add_i32 m0, s28, 0xc000
	ds_read_b128 v[188:191], v155
	ds_read_b128 v[198:201], v155 offset:1024
	ds_read_b128 v[202:205], v155 offset:2048
	ds_read_b128 v[206:209], v155 offset:3072
	ds_read_b128 v[210:213], v155 offset:4096
	ds_read_b128 v[214:217], v155 offset:5120
	ds_read_b128 v[218:221], v155 offset:6144
	ds_read_b128 v[222:225], v155 offset:7168
	global_load_lds_dwordx4 v[226:227], off
	v_lshl_add_u64 v[226:227], s[40:41], 0, v[142:143]
	s_add_i32 m0, s28, 0xe000
	s_nop 0
	global_load_lds_dwordx4 v[226:227], off
	s_waitcnt vmcnt(8)
	s_waitcnt lgkmcnt(0)
	s_barrier
	s_setprio 1
	s_waitcnt lgkmcnt(0)
	v_mfma_f32_16x16x32_bf16 v[126:129], v[148:151], v[188:191], v[126:129]
	v_mfma_f32_16x16x32_bf16 v[122:125], v[162:165], v[188:191], v[122:125]
	v_mfma_f32_16x16x32_bf16 v[110:113], v[148:151], v[202:205], v[110:113]
	v_mfma_f32_16x16x32_bf16 v[106:109], v[162:165], v[202:205], v[106:109]
	v_mfma_f32_16x16x32_bf16 v[94:97], v[148:151], v[210:213], v[94:97]
	v_mfma_f32_16x16x32_bf16 v[90:93], v[162:165], v[210:213], v[90:93]
	v_mfma_f32_16x16x32_bf16 v[78:81], v[148:151], v[218:221], v[78:81]
	v_mfma_f32_16x16x32_bf16 v[74:77], v[162:165], v[218:221], v[74:77]
	v_mfma_f32_16x16x32_bf16 v[126:129], v[158:161], v[198:201], v[126:129]
	v_mfma_f32_16x16x32_bf16 v[122:125], v[166:169], v[198:201], v[122:125]
	v_mfma_f32_16x16x32_bf16 v[110:113], v[158:161], v[206:209], v[110:113]
	v_mfma_f32_16x16x32_bf16 v[106:109], v[166:169], v[206:209], v[106:109]
	v_mfma_f32_16x16x32_bf16 v[94:97], v[158:161], v[214:217], v[94:97]
	v_mfma_f32_16x16x32_bf16 v[90:93], v[166:169], v[214:217], v[90:93]
	v_mfma_f32_16x16x32_bf16 v[78:81], v[158:161], v[222:225], v[78:81]
	v_mfma_f32_16x16x32_bf16 v[74:77], v[166:169], v[222:225], v[74:77]
	s_setprio 0
	s_setprio 1
	v_mfma_f32_16x16x32_bf16 v[118:121], v[170:173], v[188:191], v[118:121]
	v_mfma_f32_16x16x32_bf16 v[114:117], v[180:183], v[188:191], v[114:117]
	v_mfma_f32_16x16x32_bf16 v[102:105], v[170:173], v[202:205], v[102:105]
	v_mfma_f32_16x16x32_bf16 v[98:101], v[180:183], v[202:205], v[98:101]
	v_mfma_f32_16x16x32_bf16 v[86:89], v[170:173], v[210:213], v[86:89]
	v_mfma_f32_16x16x32_bf16 v[82:85], v[180:183], v[210:213], v[82:85]
	v_mfma_f32_16x16x32_bf16 v[70:73], v[170:173], v[218:221], v[70:73]
	v_mfma_f32_16x16x32_bf16 v[66:69], v[180:183], v[218:221], v[66:69]
	v_mfma_f32_16x16x32_bf16 v[118:121], v[174:177], v[198:201], v[118:121]
	v_mfma_f32_16x16x32_bf16 v[114:117], v[184:187], v[198:201], v[114:117]
	v_mfma_f32_16x16x32_bf16 v[102:105], v[174:177], v[206:209], v[102:105]
	v_mfma_f32_16x16x32_bf16 v[98:101], v[184:187], v[206:209], v[98:101]
	v_mfma_f32_16x16x32_bf16 v[86:89], v[174:177], v[214:217], v[86:89]
	v_mfma_f32_16x16x32_bf16 v[82:85], v[184:187], v[214:217], v[82:85]
	v_mfma_f32_16x16x32_bf16 v[70:73], v[174:177], v[222:225], v[70:73]
	v_mfma_f32_16x16x32_bf16 v[66:69], v[184:187], v[222:225], v[66:69]
	s_setprio 0
	s_barrier
	s_add_i32 s70, s56, s3
	v_lshl_add_u64 v[226:227], s[44:45], 0, v[132:133]
	s_mov_b32 m0, s70
	ds_read_b128 v[188:191], v155 offset:16384
	ds_read_b128 v[198:201], v155 offset:17408
	ds_read_b128 v[202:205], v155 offset:18432
	ds_read_b128 v[206:209], v155 offset:19456
	ds_read_b128 v[210:213], v155 offset:20480
	ds_read_b128 v[214:217], v155 offset:21504
	ds_read_b128 v[218:221], v155 offset:22528
	ds_read_b128 v[222:225], v155 offset:23552
	global_load_lds_dwordx4 v[226:227], off
	s_add_i32 m0, s70, 0x2000
	s_add_u32 s70, s44, 0x4000
	v_lshl_add_u64 v[226:227], s[44:45], 0, v[136:137]
	s_addc_u32 s71, s45, 0
	s_add_i32 s72, s57, s3
	global_load_lds_dwordx4 v[226:227], off
	v_lshl_add_u64 v[226:227], s[70:71], 0, v[132:133]
	s_mov_b32 m0, s72
	s_nop 0
	global_load_lds_dwordx4 v[226:227], off
	v_lshl_add_u64 v[226:227], s[70:71], 0, v[136:137]
	s_add_i32 m0, s72, 0x2000
	s_nop 0
	global_load_lds_dwordx4 v[226:227], off
	s_waitcnt vmcnt(6)
	s_waitcnt lgkmcnt(0)
	s_barrier
; #define PG8_STAGE(bufoff, gbase, voff) do { _Pragma("unroll") for (int _i = 0; _i < 2; ++_i) \
;         __builtin_amdgcn_global_load_lds((const unsigned*)((const char*)(gbase) + (voff)[_i]), (PG8_LAS unsigned*)(lds + (bufoff) + ldsw + _i * 8192), 16, 0, 0); } while (0)
; #define PG8_LDA(dst, b, h) do { _Pragma("unroll") for (int m = 0; m < 4; ++m) _Pragma("unroll") for (int k = 0; k < 2; ++k) dst[m][k] = *(const PG8_LAS bf16x8*)(lds + PG8_SA(b, h) + aoff + m * 2048 + k * 1024); } while (0)
; #define PG8_LDB(dst, b, h) do { _Pragma("unroll") for (int n = 0; n < 2; ++n) _Pragma("unroll") for (int k = 0; k < 2; ++k) dst[n][k] = *(const PG8_LAS bf16x8*)(lds + PG8_SB(b, h) + boff + n * 2048 + k * 1024); } while (0)
; #define PG8_MMA(ai, bj, At, Bt) do { __builtin_amdgcn_s_setprio(1); _Pragma("unroll") for (int m = 0; m < 4; ++m) _Pragma("unroll") for (int n = 0; n < 2; ++n) _Pragma("unroll") for (int k = 0; k < 2; ++k) \
;         acc[ai][bj][m][n] = __builtin_amdgcn_mfma_f32_16x16x32_bf16(Bt[n][k], At[m][k], acc[ai][bj][m][n], 0, 0, 0); __builtin_amdgcn_s_setprio(0); } while (0)
; #define PG8_WAIT_V(n) asm volatile("s_waitcnt vmcnt(" #n ")" ::: "memory")
; #define PG8_WAIT_L(n) asm volatile("s_waitcnt lgkmcnt(" #n ")" ::: "memory")
; #define PG8_BAR __builtin_amdgcn_s_barrier()
; #define PG8_SCHED __builtin_amdgcn_sched_barrier(0)
; template <class Epi, class Sched, bool ALIGN_EPI = false, bool SP2 = false>
; __device__ __forceinline__ void gemm_phase(PG8_LAS unsigned char* lds, const Gemm g, const Sched& S, const Epi& E) {
;     ...
;             PG8_LDA(At, 0, 1); PG8_STAGE(PG8_SB(0, 0), b2, voffB); PG8_STAGE(PG8_SB(0, 1), b2 + hstep, voffB); PG8_STAGE(PG8_SA(0, 0), a2, voffA);
;             PG8_WAIT_V(8); PG8_WAIT_L(0); PG8_BAR; PG8_MMA(1, 0, At, B0); PG8_MMA(1, 1, At, B1); PG8_BAR; PG8_SCHED;
;             PG8_LDB(B0, 1, 0); PG8_LDB(B1, 1, 1); PG8_SCHED; PG8_LDA(At, 1, 0); PG8_STAGE(PG8_SA(0, 1), a2 + hstep, voffA);
	s_setprio 1
	s_waitcnt lgkmcnt(0)
	v_mfma_f32_16x16x32_bf16 v[62:65], v[148:151], v[188:191], v[62:65]
	v_mfma_f32_16x16x32_bf16 v[58:61], v[162:165], v[188:191], v[58:61]
	v_mfma_f32_16x16x32_bf16 v[46:49], v[148:151], v[202:205], v[46:49]
	v_mfma_f32_16x16x32_bf16 v[42:45], v[162:165], v[202:205], v[42:45]
	v_mfma_f32_16x16x32_bf16 v[30:33], v[148:151], v[210:213], v[30:33]
	v_mfma_f32_16x16x32_bf16 v[26:29], v[162:165], v[210:213], v[26:29]
	v_mfma_f32_16x16x32_bf16 v[14:17], v[148:151], v[218:221], v[14:17]
	v_mfma_f32_16x16x32_bf16 v[10:13], v[162:165], v[218:221], v[10:13]
	v_mfma_f32_16x16x32_bf16 v[62:65], v[158:161], v[198:201], v[62:65]
	v_mfma_f32_16x16x32_bf16 v[58:61], v[166:169], v[198:201], v[58:61]
	v_mfma_f32_16x16x32_bf16 v[46:49], v[158:161], v[206:209], v[46:49]
	v_mfma_f32_16x16x32_bf16 v[42:45], v[166:169], v[206:209], v[42:45]
	v_mfma_f32_16x16x32_bf16 v[30:33], v[158:161], v[214:217], v[30:33]
	v_mfma_f32_16x16x32_bf16 v[26:29], v[166:169], v[214:217], v[26:29]
	v_mfma_f32_16x16x32_bf16 v[14:17], v[158:161], v[222:225], v[14:17]
	v_mfma_f32_16x16x32_bf16 v[10:13], v[166:169], v[222:225], v[10:13]
	s_setprio 0
	s_setprio 1
	v_mfma_f32_16x16x32_bf16 v[54:57], v[170:173], v[188:191], v[54:57]
	v_mfma_f32_16x16x32_bf16 v[50:53], v[180:183], v[188:191], v[50:53]
	v_mfma_f32_16x16x32_bf16 v[38:41], v[170:173], v[202:205], v[38:41]
	v_mfma_f32_16x16x32_bf16 v[34:37], v[180:183], v[202:205], v[34:37]
	v_mfma_f32_16x16x32_bf16 v[22:25], v[170:173], v[210:213], v[22:25]
	v_mfma_f32_16x16x32_bf16 v[18:21], v[180:183], v[210:213], v[18:21]
	v_mfma_f32_16x16x32_bf16 v[6:9], v[170:173], v[218:221], v[6:9]
	v_mfma_f32_16x16x32_bf16 v[2:5], v[180:183], v[218:221], v[2:5]
	v_mfma_f32_16x16x32_bf16 v[54:57], v[174:177], v[198:201], v[54:57]
	v_mfma_f32_16x16x32_bf16 v[50:53], v[184:187], v[198:201], v[50:53]
	v_mfma_f32_16x16x32_bf16 v[38:41], v[174:177], v[206:209], v[38:41]
	v_mfma_f32_16x16x32_bf16 v[34:37], v[184:187], v[206:209], v[34:37]
	v_mfma_f32_16x16x32_bf16 v[22:25], v[174:177], v[214:217], v[22:25]
	v_mfma_f32_16x16x32_bf16 v[18:21], v[184:187], v[214:217], v[18:21]
	v_mfma_f32_16x16x32_bf16 v[6:9], v[174:177], v[222:225], v[6:9]
	v_mfma_f32_16x16x32_bf16 v[2:5], v[184:187], v[222:225], v[2:5]
	s_setprio 0
	s_barrier
	s_add_i32 s70, 0, 0x18000
	v_add_u32_e32 v138, s70, v1
	s_add_i32 s71, 0, 0x1c000
	ds_read_b128 v[148:151], v138
	ds_read_b128 v[158:161], v138 offset:1024
	ds_read_b128 v[162:165], v138 offset:2048
	ds_read_b128 v[166:169], v138 offset:3072
	v_add_u32_e32 v138, s71, v1
	ds_read_b128 v[170:173], v138
	ds_read_b128 v[174:177], v138 offset:1024
	ds_read_b128 v[180:183], v138 offset:2048
	ds_read_b128 v[184:187], v138 offset:3072
	v_lshl_add_u64 v[226:227], s[46:47], 0, v[130:131]
	s_mov_b32 m0, s28
	s_nop 0
	global_load_lds_dwordx4 v[226:227], off
	v_lshl_add_u64 v[226:227], s[46:47], 0, v[134:135]
	s_mov_b32 m0, s29
	s_nop 0
	global_load_lds_dwordx4 v[226:227], off
	s_add_u32 s46, s46, 0x4000
	s_addc_u32 s47, s47, 0
	s_mov_b32 m0, s30
	v_lshl_add_u64 v[226:227], s[46:47], 0, v[130:131]
	ds_read_b128 v[188:191], v155 offset:32768
	ds_read_b128 v[198:201], v155 offset:33792
	ds_read_b128 v[202:205], v155 offset:34816
	ds_read_b128 v[206:209], v155 offset:35840
	ds_read_b128 v[210:213], v155 offset:36864
	ds_read_b128 v[214:217], v155 offset:37888
	ds_read_b128 v[218:221], v155 offset:38912
	ds_read_b128 v[222:225], v155 offset:39936
	global_load_lds_dwordx4 v[226:227], off
	v_lshl_add_u64 v[226:227], s[46:47], 0, v[134:135]
	s_mov_b32 m0, s31
	s_nop 0
	global_load_lds_dwordx4 v[226:227], off
	s_waitcnt vmcnt(8)
	s_waitcnt lgkmcnt(0)
	s_barrier
; #define PG8_STAGE(bufoff, gbase, voff) do { _Pragma("unroll") for (int _i = 0; _i < 2; ++_i) \
;         __builtin_amdgcn_global_load_lds((const unsigned*)((const char*)(gbase) + (voff)[_i]), (PG8_LAS unsigned*)(lds + (bufoff) + ldsw + _i * 8192), 16, 0, 0); } while (0)
; #define PG8_LDA(dst, b, h) do { _Pragma("unroll") for (int m = 0; m < 4; ++m) _Pragma("unroll") for (int k = 0; k < 2; ++k) dst[m][k] = *(const PG8_LAS bf16x8*)(lds + PG8_SA(b, h) + aoff + m * 2048 + k * 1024); } while (0)
; #define PG8_MMA(ai, bj, At, Bt) do { __builtin_amdgcn_s_setprio(1); _Pragma("unroll") for (int m = 0; m < 4; ++m) _Pragma("unroll") for (int n = 0; n < 2; ++n) _Pragma("unroll") for (int k = 0; k < 2; ++k) \
;         acc[ai][bj][m][n] = __builtin_amdgcn_mfma_f32_16x16x32_bf16(Bt[n][k], At[m][k], acc[ai][bj][m][n], 0, 0, 0); __builtin_amdgcn_s_setprio(0); } while (0)
; #define PG8_WAIT_V(n) asm volatile("s_waitcnt vmcnt(" #n ")" ::: "memory")
; #define PG8_WAIT_L(n) asm volatile("s_waitcnt lgkmcnt(" #n ")" ::: "memory")
; #define PG8_BAR __builtin_amdgcn_s_barrier()
; #define PG8_SCHED __builtin_amdgcn_sched_barrier(0)
; template <class Epi, class Sched, bool ALIGN_EPI = false, bool SP2 = false>
; __device__ __forceinline__ void gemm_phase(PG8_LAS unsigned char* lds, const Gemm g, const Sched& S, const Epi& E) {
;     ...
;             PG8_WAIT_V(8); PG8_WAIT_L(0); PG8_BAR; PG8_MMA(0, 0, At, B0); PG8_MMA(0, 1, At, B1); PG8_BAR; PG8_SCHED;
;             PG8_LDA(At, 1, 1); PG8_STAGE(PG8_SB(1, 0), b3, voffB); PG8_STAGE(PG8_SB(1, 1), b3 + hstep, voffB); PG8_STAGE(PG8_SA(1, 0), a3, voffA);
;             PG8_WAIT_V(8); PG8_WAIT_L(0); PG8_BAR; PG8_MMA(1, 0, At, B0); PG8_MMA(1, 1, At, B1); PG8_BAR; PG8_SCHED;
;     ...
;         if constexpr (ALIGN_EPI) { if (wr == 0) PG8_BAR; }
	s_setprio 1
	s_waitcnt lgkmcnt(0)
	v_mfma_f32_16x16x32_bf16 v[126:129], v[148:151], v[188:191], v[126:129]
	v_mfma_f32_16x16x32_bf16 v[122:125], v[162:165], v[188:191], v[122:125]
	v_mfma_f32_16x16x32_bf16 v[110:113], v[148:151], v[202:205], v[110:113]
	v_mfma_f32_16x16x32_bf16 v[106:109], v[162:165], v[202:205], v[106:109]
	v_mfma_f32_16x16x32_bf16 v[94:97], v[148:151], v[210:213], v[94:97]
	v_mfma_f32_16x16x32_bf16 v[90:93], v[162:165], v[210:213], v[90:93]
	v_mfma_f32_16x16x32_bf16 v[78:81], v[148:151], v[218:221], v[78:81]
	v_mfma_f32_16x16x32_bf16 v[74:77], v[162:165], v[218:221], v[74:77]
	v_mfma_f32_16x16x32_bf16 v[126:129], v[158:161], v[198:201], v[126:129]
	v_mfma_f32_16x16x32_bf16 v[122:125], v[166:169], v[198:201], v[122:125]
	v_mfma_f32_16x16x32_bf16 v[110:113], v[158:161], v[206:209], v[110:113]
	v_mfma_f32_16x16x32_bf16 v[106:109], v[166:169], v[206:209], v[106:109]
	v_mfma_f32_16x16x32_bf16 v[94:97], v[158:161], v[214:217], v[94:97]
	v_mfma_f32_16x16x32_bf16 v[90:93], v[166:169], v[214:217], v[90:93]
	v_mfma_f32_16x16x32_bf16 v[78:81], v[158:161], v[222:225], v[78:81]
	v_mfma_f32_16x16x32_bf16 v[74:77], v[166:169], v[222:225], v[74:77]
	s_setprio 0
	s_setprio 1
	v_mfma_f32_16x16x32_bf16 v[118:121], v[170:173], v[188:191], v[118:121]
	v_mfma_f32_16x16x32_bf16 v[114:117], v[180:183], v[188:191], v[114:117]
	v_mfma_f32_16x16x32_bf16 v[102:105], v[170:173], v[202:205], v[102:105]
	v_mfma_f32_16x16x32_bf16 v[98:101], v[180:183], v[202:205], v[98:101]
	v_mfma_f32_16x16x32_bf16 v[86:89], v[170:173], v[210:213], v[86:89]
	v_mfma_f32_16x16x32_bf16 v[82:85], v[180:183], v[210:213], v[82:85]
	v_mfma_f32_16x16x32_bf16 v[70:73], v[170:173], v[218:221], v[70:73]
	v_mfma_f32_16x16x32_bf16 v[66:69], v[180:183], v[218:221], v[66:69]
	v_mfma_f32_16x16x32_bf16 v[118:121], v[174:177], v[198:201], v[118:121]
	v_mfma_f32_16x16x32_bf16 v[114:117], v[184:187], v[198:201], v[114:117]
	v_mfma_f32_16x16x32_bf16 v[102:105], v[174:177], v[206:209], v[102:105]
	v_mfma_f32_16x16x32_bf16 v[98:101], v[184:187], v[206:209], v[98:101]
	v_mfma_f32_16x16x32_bf16 v[86:89], v[174:177], v[214:217], v[86:89]
	v_mfma_f32_16x16x32_bf16 v[82:85], v[184:187], v[214:217], v[82:85]
	v_mfma_f32_16x16x32_bf16 v[70:73], v[174:177], v[222:225], v[70:73]
	v_mfma_f32_16x16x32_bf16 v[66:69], v[184:187], v[222:225], v[66:69]
	s_setprio 0
	s_barrier
	s_add_u32 s46, s44, 0x8000
	s_addc_u32 s47, s45, 0
	s_add_i32 s70, s70, s3
	v_lshl_add_u64 v[226:227], s[46:47], 0, v[132:133]
	s_mov_b32 m0, s70
	ds_read_b128 v[188:191], v155 offset:49152
	ds_read_b128 v[198:201], v155 offset:50176
	ds_read_b128 v[202:205], v155 offset:51200
	ds_read_b128 v[206:209], v155 offset:52224
	ds_read_b128 v[210:213], v155 offset:53248
	ds_read_b128 v[214:217], v155 offset:54272
	ds_read_b128 v[218:221], v155 offset:55296
	ds_read_b128 v[222:225], v155 offset:56320
	global_load_lds_dwordx4 v[226:227], off
	s_add_i32 m0, s70, 0x2000
	s_add_u32 s44, s44, 0xc000
	v_lshl_add_u64 v[226:227], s[46:47], 0, v[136:137]
	s_addc_u32 s45, s45, 0
	s_add_i32 s46, s71, s3
	global_load_lds_dwordx4 v[226:227], off
	v_lshl_add_u64 v[226:227], s[44:45], 0, v[132:133]
	s_mov_b32 m0, s46
	s_nop 0
	global_load_lds_dwordx4 v[226:227], off
	v_lshl_add_u64 v[226:227], s[44:45], 0, v[136:137]
	s_add_i32 m0, s46, 0x2000
	s_nop 0
	global_load_lds_dwordx4 v[226:227], off
	s_waitcnt vmcnt(6)
	s_waitcnt lgkmcnt(0)
	s_barrier
	s_setprio 1
	s_waitcnt lgkmcnt(0)
	v_mfma_f32_16x16x32_bf16 v[62:65], v[148:151], v[188:191], v[62:65]
	v_mfma_f32_16x16x32_bf16 v[58:61], v[162:165], v[188:191], v[58:61]
	v_mfma_f32_16x16x32_bf16 v[46:49], v[148:151], v[202:205], v[46:49]
	v_mfma_f32_16x16x32_bf16 v[42:45], v[162:165], v[202:205], v[42:45]
	v_mfma_f32_16x16x32_bf16 v[30:33], v[148:151], v[210:213], v[30:33]
	v_mfma_f32_16x16x32_bf16 v[26:29], v[162:165], v[210:213], v[26:29]
	v_mfma_f32_16x16x32_bf16 v[14:17], v[148:151], v[218:221], v[14:17]
	v_mfma_f32_16x16x32_bf16 v[10:13], v[162:165], v[218:221], v[10:13]
	v_mfma_f32_16x16x32_bf16 v[62:65], v[158:161], v[198:201], v[62:65]
	v_mfma_f32_16x16x32_bf16 v[58:61], v[166:169], v[198:201], v[58:61]
	v_mfma_f32_16x16x32_bf16 v[46:49], v[158:161], v[206:209], v[46:49]
	v_mfma_f32_16x16x32_bf16 v[42:45], v[166:169], v[206:209], v[42:45]
	v_mfma_f32_16x16x32_bf16 v[30:33], v[158:161], v[214:217], v[30:33]
	v_mfma_f32_16x16x32_bf16 v[26:29], v[166:169], v[214:217], v[26:29]
	v_mfma_f32_16x16x32_bf16 v[14:17], v[158:161], v[222:225], v[14:17]
	v_mfma_f32_16x16x32_bf16 v[10:13], v[166:169], v[222:225], v[10:13]
	s_setprio 0
	s_setprio 1
	v_mfma_f32_16x16x32_bf16 v[54:57], v[170:173], v[188:191], v[54:57]
	v_mfma_f32_16x16x32_bf16 v[50:53], v[180:183], v[188:191], v[50:53]
	v_mfma_f32_16x16x32_bf16 v[38:41], v[170:173], v[202:205], v[38:41]
	v_mfma_f32_16x16x32_bf16 v[34:37], v[180:183], v[202:205], v[34:37]
	v_mfma_f32_16x16x32_bf16 v[22:25], v[170:173], v[210:213], v[22:25]
	v_mfma_f32_16x16x32_bf16 v[18:21], v[180:183], v[210:213], v[18:21]
	v_mfma_f32_16x16x32_bf16 v[6:9], v[170:173], v[218:221], v[6:9]
	v_mfma_f32_16x16x32_bf16 v[2:5], v[180:183], v[218:221], v[2:5]
	v_mfma_f32_16x16x32_bf16 v[54:57], v[174:177], v[198:201], v[54:57]
	v_mfma_f32_16x16x32_bf16 v[50:53], v[184:187], v[198:201], v[50:53]
	v_mfma_f32_16x16x32_bf16 v[38:41], v[174:177], v[206:209], v[38:41]
	v_mfma_f32_16x16x32_bf16 v[34:37], v[184:187], v[206:209], v[34:37]
	v_mfma_f32_16x16x32_bf16 v[22:25], v[174:177], v[214:217], v[22:25]
	v_mfma_f32_16x16x32_bf16 v[18:21], v[184:187], v[214:217], v[18:21]
	v_mfma_f32_16x16x32_bf16 v[6:9], v[174:177], v[222:225], v[6:9]
	v_mfma_f32_16x16x32_bf16 v[2:5], v[184:187], v[222:225], v[2:5]
	s_setprio 0
	s_barrier
	s_add_i32 s69, s69, 2
	s_add_u32 s40, s40, 0x10000
	s_addc_u32 s41, s41, 0
	s_add_u32 s67, s67, 0x10000
	s_addc_u32 s68, s68, 0
	s_cmp_gt_u32 s69, 61
	s_cbranch_scc0 .LBB0_840
	s_and_b64 vcc, exec, s[14:15]
	s_cbranch_vccz .LBB0_843
	s_barrier

; #define PG8_STAGE(bufoff, gbase, voff) do { _Pragma("unroll") for (int _i = 0; _i < 2; ++_i) \
;         __builtin_amdgcn_global_load_lds((const unsigned*)((const char*)(gbase) + (voff)[_i]), (PG8_LAS unsigned*)(lds + (bufoff) + ldsw + _i * 8192), 16, 0, 0); } while (0)
; #define PG8_LDA(dst, b, h) do { _Pragma("unroll") for (int m = 0; m < 4; ++m) _Pragma("unroll") for (int k = 0; k < 2; ++k) dst[m][k] = *(const PG8_LAS bf16x8*)(lds + PG8_SA(b, h) + aoff + m * 2048 + k * 1024); } while (0)
; #define PG8_LDB(dst, b, h) do { _Pragma("unroll") for (int n = 0; n < 2; ++n) _Pragma("unroll") for (int k = 0; k < 2; ++k) dst[n][k] = *(const PG8_LAS bf16x8*)(lds + PG8_SB(b, h) + boff + n * 2048 + k * 1024); } while (0)
; #define PG8_MMA(ai, bj, At, Bt) do { __builtin_amdgcn_s_setprio(1); _Pragma("unroll") for (int m = 0; m < 4; ++m) _Pragma("unroll") for (int n = 0; n < 2; ++n) _Pragma("unroll") for (int k = 0; k < 2; ++k) \
;         acc[ai][bj][m][n] = __builtin_amdgcn_mfma_f32_16x16x32_bf16(Bt[n][k], At[m][k], acc[ai][bj][m][n], 0, 0, 0); __builtin_amdgcn_s_setprio(0); } while (0)
; #define PG8_WAIT_V(n) asm volatile("s_waitcnt vmcnt(" #n ")" ::: "memory")
; #define PG8_WAIT_L(n) asm volatile("s_waitcnt lgkmcnt(" #n ")" ::: "memory")
; #define PG8_BAR __builtin_amdgcn_s_barrier()
; #define PG8_SCHED __builtin_amdgcn_sched_barrier(0)
; template <class Epi, class Sched, bool ALIGN_EPI = false, bool SP2 = false>
; __device__ __forceinline__ void gemm_phase(PG8_LAS unsigned char* lds, const Gemm g, const Sched& S, const Epi& E) {
;     ...
;             const bool last = (t == nt - 2);
;             const char* a1 = cA + (size_t)(t + 1) * kstep;
;             const char* a2 = last ? nA : cA + (size_t)(t + 2) * kstep; const char* b2 = last ? nB : cB + (size_t)(t + 2) * kstep;
;             const char* a3 = a2 + kstep; const char* b3 = b2 + kstep;
;             if (last && has_next) S.a_ready(nxt);
;             if constexpr (SP2) {
;             PG8_LDB(B0, 0, 0); PG8_LDB(B1, 0, 1); PG8_SCHED; PG8_LDA(At, 0, 0); PG8_STAGE(PG8_SA(1, 1), a1 + hstep, voffA);
;             PG8_WAIT_V(8); PG8_WAIT_L(0); PG8_BAR; PG8_MMA(0, 0, At, B0); PG8_MMA(0, 1, At, B1); PG8_BAR; PG8_SCHED;
;             PG8_LDA(At, 0, 1); PG8_STAGE(PG8_SB(0, 0), b2, voffB); PG8_STAGE(PG8_SB(0, 1), b2 + hstep, voffB); PG8_STAGE(PG8_SA(0, 0), a2, voffA);
.LBB0_924:
	ds_read_b128 v[148:151], v153
	ds_read_b128 v[156:159], v153 offset:1024
	ds_read_b128 v[160:163], v153 offset:2048
	ds_read_b128 v[164:167], v153 offset:3072
	ds_read_b128 v[168:171], v154
	ds_read_b128 v[172:175], v154 offset:1024
	ds_read_b128 v[180:183], v154 offset:2048
	ds_read_b128 v[184:187], v154 offset:3072
	s_add_u32 s36, s26, 0x4000
	s_addc_u32 s37, s27, 0
	s_cmpk_eq_i32 s64, 0xa8
	s_cselect_b32 s40, s4, s36
	s_cselect_b32 s41, s5, s37
	s_cselect_b32 s38, s22, s62
	s_cselect_b32 s39, s23, s63
	s_sub_u32 s36, s26, 0x4000
	s_subb_u32 s37, s27, 0
	v_lshl_add_u64 v[176:177], s[36:37], 0, v[130:131]
	s_mov_b32 m0, s45
	s_nop 0
	global_load_lds_dwordx4 v[176:177], off
	v_lshl_add_u64 v[176:177], s[36:37], 0, v[134:135]
	s_mov_b32 m0, s46
	s_nop 0
	global_load_lds_dwordx4 v[176:177], off
	v_lshl_add_u64 v[176:177], s[26:27], 0, v[138:139]
	s_add_i32 m0, s29, 0xc000
	ds_read_b128 v[188:191], v155
	ds_read_b128 v[196:199], v155 offset:1024
	ds_read_b128 v[200:203], v155 offset:2048
	ds_read_b128 v[204:207], v155 offset:3072
	ds_read_b128 v[208:211], v155 offset:4096
	ds_read_b128 v[212:215], v155 offset:5120
	ds_read_b128 v[216:219], v155 offset:6144
	ds_read_b128 v[220:223], v155 offset:7168
	global_load_lds_dwordx4 v[176:177], off
	v_lshl_add_u64 v[176:177], s[26:27], 0, v[142:143]
	s_add_i32 m0, s29, 0xe000
	s_nop 0
	global_load_lds_dwordx4 v[176:177], off
	s_waitcnt vmcnt(8)
	s_waitcnt lgkmcnt(0)
	s_barrier
	s_setprio 1
	s_waitcnt lgkmcnt(0)
	v_mfma_f32_16x16x32_bf16 v[126:129], v[148:151], v[188:191], v[126:129]
	v_mfma_f32_16x16x32_bf16 v[122:125], v[160:163], v[188:191], v[122:125]
	v_mfma_f32_16x16x32_bf16 v[110:113], v[148:151], v[200:203], v[110:113]
	v_mfma_f32_16x16x32_bf16 v[106:109], v[160:163], v[200:203], v[106:109]
	v_mfma_f32_16x16x32_bf16 v[94:97], v[148:151], v[208:211], v[94:97]
	v_mfma_f32_16x16x32_bf16 v[90:93], v[160:163], v[208:211], v[90:93]
	v_mfma_f32_16x16x32_bf16 v[78:81], v[148:151], v[216:219], v[78:81]
	v_mfma_f32_16x16x32_bf16 v[74:77], v[160:163], v[216:219], v[74:77]
	v_mfma_f32_16x16x32_bf16 v[126:129], v[156:159], v[196:199], v[126:129]
	v_mfma_f32_16x16x32_bf16 v[122:125], v[164:167], v[196:199], v[122:125]
	v_mfma_f32_16x16x32_bf16 v[110:113], v[156:159], v[204:207], v[110:113]
	v_mfma_f32_16x16x32_bf16 v[106:109], v[164:167], v[204:207], v[106:109]
	v_mfma_f32_16x16x32_bf16 v[94:97], v[156:159], v[212:215], v[94:97]
	v_mfma_f32_16x16x32_bf16 v[90:93], v[164:167], v[212:215], v[90:93]
	v_mfma_f32_16x16x32_bf16 v[78:81], v[156:159], v[220:223], v[78:81]
	v_mfma_f32_16x16x32_bf16 v[74:77], v[164:167], v[220:223], v[74:77]
	s_setprio 0
	s_setprio 1
	v_mfma_f32_16x16x32_bf16 v[118:121], v[168:171], v[188:191], v[118:121]
	v_mfma_f32_16x16x32_bf16 v[114:117], v[180:183], v[188:191], v[114:117]
	v_mfma_f32_16x16x32_bf16 v[102:105], v[168:171], v[200:203], v[102:105]
	v_mfma_f32_16x16x32_bf16 v[98:101], v[180:183], v[200:203], v[98:101]
	v_mfma_f32_16x16x32_bf16 v[86:89], v[168:171], v[208:211], v[86:89]
	v_mfma_f32_16x16x32_bf16 v[82:85], v[180:183], v[208:211], v[82:85]
	v_mfma_f32_16x16x32_bf16 v[70:73], v[168:171], v[216:219], v[70:73]
	v_mfma_f32_16x16x32_bf16 v[66:69], v[180:183], v[216:219], v[66:69]
	v_mfma_f32_16x16x32_bf16 v[118:121], v[172:175], v[196:199], v[118:121]
	v_mfma_f32_16x16x32_bf16 v[114:117], v[184:187], v[196:199], v[114:117]
	v_mfma_f32_16x16x32_bf16 v[102:105], v[172:175], v[204:207], v[102:105]
	v_mfma_f32_16x16x32_bf16 v[98:101], v[184:187], v[204:207], v[98:101]
	v_mfma_f32_16x16x32_bf16 v[86:89], v[172:175], v[212:215], v[86:89]
	v_mfma_f32_16x16x32_bf16 v[82:85], v[184:187], v[212:215], v[82:85]
	v_mfma_f32_16x16x32_bf16 v[70:73], v[172:175], v[220:223], v[70:73]
	v_mfma_f32_16x16x32_bf16 v[66:69], v[184:187], v[220:223], v[66:69]
	s_setprio 0
	s_barrier
	s_add_i32 s65, s47, s3
	v_lshl_add_u64 v[176:177], s[38:39], 0, v[132:133]
	s_mov_b32 m0, s65
	ds_read_b128 v[188:191], v155 offset:16384
	ds_read_b128 v[196:199], v155 offset:17408
	ds_read_b128 v[200:203], v155 offset:18432
	ds_read_b128 v[204:207], v155 offset:19456
	ds_read_b128 v[208:211], v155 offset:20480
	ds_read_b128 v[212:215], v155 offset:21504
	ds_read_b128 v[216:219], v155 offset:22528
	ds_read_b128 v[220:223], v155 offset:23552
	global_load_lds_dwordx4 v[176:177], off
	s_add_i32 m0, s65, 0x2000
	s_add_u32 s66, s38, 0x4000
	v_lshl_add_u64 v[176:177], s[38:39], 0, v[136:137]
	s_addc_u32 s67, s39, 0
	s_add_i32 s65, s48, s3
	global_load_lds_dwordx4 v[176:177], off
	v_lshl_add_u64 v[176:177], s[66:67], 0, v[132:133]
	s_mov_b32 m0, s65
	s_nop 0
	global_load_lds_dwordx4 v[176:177], off
	v_lshl_add_u64 v[176:177], s[66:67], 0, v[136:137]
	s_add_i32 m0, s65, 0x2000
	s_nop 0
	global_load_lds_dwordx4 v[176:177], off
	s_waitcnt vmcnt(6)
	s_waitcnt lgkmcnt(0)
	s_barrier
; #define PG8_STAGE(bufoff, gbase, voff) do { _Pragma("unroll") for (int _i = 0; _i < 2; ++_i) \
;         __builtin_amdgcn_global_load_lds((const unsigned*)((const char*)(gbase) + (voff)[_i]), (PG8_LAS unsigned*)(lds + (bufoff) + ldsw + _i * 8192), 16, 0, 0); } while (0)
; #define PG8_LDA(dst, b, h) do { _Pragma("unroll") for (int m = 0; m < 4; ++m) _Pragma("unroll") for (int k = 0; k < 2; ++k) dst[m][k] = *(const PG8_LAS bf16x8*)(lds + PG8_SA(b, h) + aoff + m * 2048 + k * 1024); } while (0)
; #define PG8_LDB(dst, b, h) do { _Pragma("unroll") for (int n = 0; n < 2; ++n) _Pragma("unroll") for (int k = 0; k < 2; ++k) dst[n][k] = *(const PG8_LAS bf16x8*)(lds + PG8_SB(b, h) + boff + n * 2048 + k * 1024); } while (0)
; #define PG8_MMA(ai, bj, At, Bt) do { __builtin_amdgcn_s_setprio(1); _Pragma("unroll") for (int m = 0; m < 4; ++m) _Pragma("unroll") for (int n = 0; n < 2; ++n) _Pragma("unroll") for (int k = 0; k < 2; ++k) \
;         acc[ai][bj][m][n] = __builtin_amdgcn_mfma_f32_16x16x32_bf16(Bt[n][k], At[m][k], acc[ai][bj][m][n], 0, 0, 0); __builtin_amdgcn_s_setprio(0); } while (0)
; #define PG8_WAIT_V(n) asm volatile("s_waitcnt vmcnt(" #n ")" ::: "memory")
; #define PG8_WAIT_L(n) asm volatile("s_waitcnt lgkmcnt(" #n ")" ::: "memory")
; #define PG8_BAR __builtin_amdgcn_s_barrier()
; #define PG8_SCHED __builtin_amdgcn_sched_barrier(0)
; template <class Epi, class Sched, bool ALIGN_EPI = false, bool SP2 = false>
; __device__ __forceinline__ void gemm_phase(PG8_LAS unsigned char* lds, const Gemm g, const Sched& S, const Epi& E) {
;     ...
;             PG8_LDA(At, 0, 1); PG8_STAGE(PG8_SB(0, 0), b2, voffB); PG8_STAGE(PG8_SB(0, 1), b2 + hstep, voffB); PG8_STAGE(PG8_SA(0, 0), a2, voffA);
;             PG8_WAIT_V(8); PG8_WAIT_L(0); PG8_BAR; PG8_MMA(1, 0, At, B0); PG8_MMA(1, 1, At, B1); PG8_BAR; PG8_SCHED;
;             PG8_LDB(B0, 1, 0); PG8_LDB(B1, 1, 1); PG8_SCHED; PG8_LDA(At, 1, 0); PG8_STAGE(PG8_SA(0, 1), a2 + hstep, voffA);
	s_setprio 1
	s_waitcnt lgkmcnt(0)
	v_mfma_f32_16x16x32_bf16 v[62:65], v[148:151], v[188:191], v[62:65]
	v_mfma_f32_16x16x32_bf16 v[58:61], v[160:163], v[188:191], v[58:61]
	v_mfma_f32_16x16x32_bf16 v[46:49], v[148:151], v[200:203], v[46:49]
	v_mfma_f32_16x16x32_bf16 v[42:45], v[160:163], v[200:203], v[42:45]
	v_mfma_f32_16x16x32_bf16 v[30:33], v[148:151], v[208:211], v[30:33]
	v_mfma_f32_16x16x32_bf16 v[26:29], v[160:163], v[208:211], v[26:29]
	v_mfma_f32_16x16x32_bf16 v[14:17], v[148:151], v[216:219], v[14:17]
	v_mfma_f32_16x16x32_bf16 v[10:13], v[160:163], v[216:219], v[10:13]
	v_mfma_f32_16x16x32_bf16 v[62:65], v[156:159], v[196:199], v[62:65]
	v_mfma_f32_16x16x32_bf16 v[58:61], v[164:167], v[196:199], v[58:61]
	v_mfma_f32_16x16x32_bf16 v[46:49], v[156:159], v[204:207], v[46:49]
	v_mfma_f32_16x16x32_bf16 v[42:45], v[164:167], v[204:207], v[42:45]
	v_mfma_f32_16x16x32_bf16 v[30:33], v[156:159], v[212:215], v[30:33]
	v_mfma_f32_16x16x32_bf16 v[26:29], v[164:167], v[212:215], v[26:29]
	v_mfma_f32_16x16x32_bf16 v[14:17], v[156:159], v[220:223], v[14:17]
	v_mfma_f32_16x16x32_bf16 v[10:13], v[164:167], v[220:223], v[10:13]
	s_setprio 0
	s_setprio 1
	v_mfma_f32_16x16x32_bf16 v[54:57], v[168:171], v[188:191], v[54:57]
	v_mfma_f32_16x16x32_bf16 v[50:53], v[180:183], v[188:191], v[50:53]
	v_mfma_f32_16x16x32_bf16 v[38:41], v[168:171], v[200:203], v[38:41]
	v_mfma_f32_16x16x32_bf16 v[34:37], v[180:183], v[200:203], v[34:37]
	v_mfma_f32_16x16x32_bf16 v[22:25], v[168:171], v[208:211], v[22:25]
	v_mfma_f32_16x16x32_bf16 v[18:21], v[180:183], v[208:211], v[18:21]
	v_mfma_f32_16x16x32_bf16 v[6:9], v[168:171], v[216:219], v[6:9]
	v_mfma_f32_16x16x32_bf16 v[2:5], v[180:183], v[216:219], v[2:5]
	v_mfma_f32_16x16x32_bf16 v[54:57], v[172:175], v[196:199], v[54:57]
	v_mfma_f32_16x16x32_bf16 v[50:53], v[184:187], v[196:199], v[50:53]
	v_mfma_f32_16x16x32_bf16 v[38:41], v[172:175], v[204:207], v[38:41]
	v_mfma_f32_16x16x32_bf16 v[34:37], v[184:187], v[204:207], v[34:37]
	v_mfma_f32_16x16x32_bf16 v[22:25], v[172:175], v[212:215], v[22:25]
	v_mfma_f32_16x16x32_bf16 v[18:21], v[184:187], v[212:215], v[18:21]
	v_mfma_f32_16x16x32_bf16 v[6:9], v[172:175], v[220:223], v[6:9]
	v_mfma_f32_16x16x32_bf16 v[2:5], v[184:187], v[220:223], v[2:5]
	s_setprio 0
	s_barrier
	s_add_i32 s65, 0, 0x18000
	v_add_u32_e32 v140, s65, v152
	s_add_i32 s66, 0, 0x1c000
	ds_read_b128 v[148:151], v140
	ds_read_b128 v[156:159], v140 offset:1024
	ds_read_b128 v[160:163], v140 offset:2048
	ds_read_b128 v[164:167], v140 offset:3072
	v_add_u32_e32 v140, s66, v152
	ds_read_b128 v[168:171], v140
	ds_read_b128 v[172:175], v140 offset:1024
	ds_read_b128 v[180:183], v140 offset:2048
	ds_read_b128 v[184:187], v140 offset:3072
	v_lshl_add_u64 v[176:177], s[40:41], 0, v[130:131]
	s_mov_b32 m0, s29
	s_nop 0
	global_load_lds_dwordx4 v[176:177], off
	v_lshl_add_u64 v[176:177], s[40:41], 0, v[134:135]
	s_mov_b32 m0, s30
	s_nop 0
	global_load_lds_dwordx4 v[176:177], off
	s_add_u32 s40, s40, 0x4000
	s_addc_u32 s41, s41, 0
	s_mov_b32 m0, s31
	v_lshl_add_u64 v[176:177], s[40:41], 0, v[130:131]
	ds_read_b128 v[188:191], v155 offset:32768
	ds_read_b128 v[196:199], v155 offset:33792
	ds_read_b128 v[200:203], v155 offset:34816
	ds_read_b128 v[204:207], v155 offset:35840
	ds_read_b128 v[208:211], v155 offset:36864
	ds_read_b128 v[212:215], v155 offset:37888
	ds_read_b128 v[216:219], v155 offset:38912
	ds_read_b128 v[220:223], v155 offset:39936
	global_load_lds_dwordx4 v[176:177], off
	v_lshl_add_u64 v[176:177], s[40:41], 0, v[134:135]
	s_mov_b32 m0, s33
	s_nop 0
	global_load_lds_dwordx4 v[176:177], off
	s_waitcnt vmcnt(8)
	s_waitcnt lgkmcnt(0)
	s_barrier
; #define PG8_STAGE(bufoff, gbase, voff) do { _Pragma("unroll") for (int _i = 0; _i < 2; ++_i) \
;         __builtin_amdgcn_global_load_lds((const unsigned*)((const char*)(gbase) + (voff)[_i]), (PG8_LAS unsigned*)(lds + (bufoff) + ldsw + _i * 8192), 16, 0, 0); } while (0)
; #define PG8_LDA(dst, b, h) do { _Pragma("unroll") for (int m = 0; m < 4; ++m) _Pragma("unroll") for (int k = 0; k < 2; ++k) dst[m][k] = *(const PG8_LAS bf16x8*)(lds + PG8_SA(b, h) + aoff + m * 2048 + k * 1024); } while (0)
; #define PG8_MMA(ai, bj, At, Bt) do { __builtin_amdgcn_s_setprio(1); _Pragma("unroll") for (int m = 0; m < 4; ++m) _Pragma("unroll") for (int n = 0; n < 2; ++n) _Pragma("unroll") for (int k = 0; k < 2; ++k) \
;         acc[ai][bj][m][n] = __builtin_amdgcn_mfma_f32_16x16x32_bf16(Bt[n][k], At[m][k], acc[ai][bj][m][n], 0, 0, 0); __builtin_amdgcn_s_setprio(0); } while (0)
; #define PG8_WAIT_V(n) asm volatile("s_waitcnt vmcnt(" #n ")" ::: "memory")
; #define PG8_WAIT_L(n) asm volatile("s_waitcnt lgkmcnt(" #n ")" ::: "memory")
; #define PG8_BAR __builtin_amdgcn_s_barrier()
; #define PG8_SCHED __builtin_amdgcn_sched_barrier(0)
; template <class Epi, class Sched, bool ALIGN_EPI = false, bool SP2 = false>
; __device__ __forceinline__ void gemm_phase(PG8_LAS unsigned char* lds, const Gemm g, const Sched& S, const Epi& E) {
;     ...
;             PG8_WAIT_V(8); PG8_WAIT_L(0); PG8_BAR; PG8_MMA(0, 0, At, B0); PG8_MMA(0, 1, At, B1); PG8_BAR; PG8_SCHED;
;             PG8_LDA(At, 1, 1); PG8_STAGE(PG8_SB(1, 0), b3, voffB); PG8_STAGE(PG8_SB(1, 1), b3 + hstep, voffB); PG8_STAGE(PG8_SA(1, 0), a3, voffA);
;             PG8_WAIT_V(8); PG8_WAIT_L(0); PG8_BAR; PG8_MMA(1, 0, At, B0); PG8_MMA(1, 1, At, B1); PG8_BAR; PG8_SCHED;
;     ...
;         if constexpr (ALIGN_EPI) { if (wr == 0) PG8_BAR; }
	s_setprio 1
	s_waitcnt lgkmcnt(0)
	v_mfma_f32_16x16x32_bf16 v[126:129], v[148:151], v[188:191], v[126:129]
	v_mfma_f32_16x16x32_bf16 v[122:125], v[160:163], v[188:191], v[122:125]
	v_mfma_f32_16x16x32_bf16 v[110:113], v[148:151], v[200:203], v[110:113]
	v_mfma_f32_16x16x32_bf16 v[106:109], v[160:163], v[200:203], v[106:109]
	v_mfma_f32_16x16x32_bf16 v[94:97], v[148:151], v[208:211], v[94:97]
	v_mfma_f32_16x16x32_bf16 v[90:93], v[160:163], v[208:211], v[90:93]
	v_mfma_f32_16x16x32_bf16 v[78:81], v[148:151], v[216:219], v[78:81]
	v_mfma_f32_16x16x32_bf16 v[74:77], v[160:163], v[216:219], v[74:77]
	v_mfma_f32_16x16x32_bf16 v[126:129], v[156:159], v[196:199], v[126:129]
	v_mfma_f32_16x16x32_bf16 v[122:125], v[164:167], v[196:199], v[122:125]
	v_mfma_f32_16x16x32_bf16 v[110:113], v[156:159], v[204:207], v[110:113]
	v_mfma_f32_16x16x32_bf16 v[106:109], v[164:167], v[204:207], v[106:109]
	v_mfma_f32_16x16x32_bf16 v[94:97], v[156:159], v[212:215], v[94:97]
	v_mfma_f32_16x16x32_bf16 v[90:93], v[164:167], v[212:215], v[90:93]
	v_mfma_f32_16x16x32_bf16 v[78:81], v[156:159], v[220:223], v[78:81]
	v_mfma_f32_16x16x32_bf16 v[74:77], v[164:167], v[220:223], v[74:77]
	s_setprio 0
	s_setprio 1
	v_mfma_f32_16x16x32_bf16 v[118:121], v[168:171], v[188:191], v[118:121]
	v_mfma_f32_16x16x32_bf16 v[114:117], v[180:183], v[188:191], v[114:117]
	v_mfma_f32_16x16x32_bf16 v[102:105], v[168:171], v[200:203], v[102:105]
	v_mfma_f32_16x16x32_bf16 v[98:101], v[180:183], v[200:203], v[98:101]
	v_mfma_f32_16x16x32_bf16 v[86:89], v[168:171], v[208:211], v[86:89]
	v_mfma_f32_16x16x32_bf16 v[82:85], v[180:183], v[208:211], v[82:85]
	v_mfma_f32_16x16x32_bf16 v[70:73], v[168:171], v[216:219], v[70:73]
	v_mfma_f32_16x16x32_bf16 v[66:69], v[180:183], v[216:219], v[66:69]
	v_mfma_f32_16x16x32_bf16 v[118:121], v[172:175], v[196:199], v[118:121]
	v_mfma_f32_16x16x32_bf16 v[114:117], v[184:187], v[196:199], v[114:117]
	v_mfma_f32_16x16x32_bf16 v[102:105], v[172:175], v[204:207], v[102:105]
	v_mfma_f32_16x16x32_bf16 v[98:101], v[184:187], v[204:207], v[98:101]
	v_mfma_f32_16x16x32_bf16 v[86:89], v[172:175], v[212:215], v[86:89]
	v_mfma_f32_16x16x32_bf16 v[82:85], v[184:187], v[212:215], v[82:85]
	v_mfma_f32_16x16x32_bf16 v[70:73], v[172:175], v[220:223], v[70:73]
	v_mfma_f32_16x16x32_bf16 v[66:69], v[184:187], v[220:223], v[66:69]
	s_setprio 0
	s_barrier
	s_add_u32 s40, s38, 0x8000
	s_addc_u32 s41, s39, 0
	s_add_i32 s65, s65, s3
	v_lshl_add_u64 v[176:177], s[40:41], 0, v[132:133]
	s_mov_b32 m0, s65
	ds_read_b128 v[188:191], v155 offset:49152
	ds_read_b128 v[196:199], v155 offset:50176
	ds_read_b128 v[200:203], v155 offset:51200
	ds_read_b128 v[204:207], v155 offset:52224
	ds_read_b128 v[208:211], v155 offset:53248
	ds_read_b128 v[212:215], v155 offset:54272
	ds_read_b128 v[216:219], v155 offset:55296
	ds_read_b128 v[220:223], v155 offset:56320
	global_load_lds_dwordx4 v[176:177], off
	s_add_i32 m0, s65, 0x2000
	s_add_u32 s38, s38, 0xc000
	v_lshl_add_u64 v[176:177], s[40:41], 0, v[136:137]
	s_addc_u32 s39, s39, 0
	s_add_i32 s40, s66, s3
	global_load_lds_dwordx4 v[176:177], off
	v_lshl_add_u64 v[176:177], s[38:39], 0, v[132:133]
	s_mov_b32 m0, s40
	s_nop 0
	global_load_lds_dwordx4 v[176:177], off
	v_lshl_add_u64 v[176:177], s[38:39], 0, v[136:137]
	s_add_i32 m0, s40, 0x2000
	s_nop 0
	global_load_lds_dwordx4 v[176:177], off
	s_waitcnt vmcnt(6)
	s_waitcnt lgkmcnt(0)
	s_barrier
	s_setprio 1
	s_waitcnt lgkmcnt(0)
	v_mfma_f32_16x16x32_bf16 v[62:65], v[148:151], v[188:191], v[62:65]
	v_mfma_f32_16x16x32_bf16 v[58:61], v[160:163], v[188:191], v[58:61]
	v_mfma_f32_16x16x32_bf16 v[46:49], v[148:151], v[200:203], v[46:49]
	v_mfma_f32_16x16x32_bf16 v[42:45], v[160:163], v[200:203], v[42:45]
	v_mfma_f32_16x16x32_bf16 v[30:33], v[148:151], v[208:211], v[30:33]
	v_mfma_f32_16x16x32_bf16 v[26:29], v[160:163], v[208:211], v[26:29]
	v_mfma_f32_16x16x32_bf16 v[14:17], v[148:151], v[216:219], v[14:17]
	v_mfma_f32_16x16x32_bf16 v[10:13], v[160:163], v[216:219], v[10:13]
	v_mfma_f32_16x16x32_bf16 v[62:65], v[156:159], v[196:199], v[62:65]
	v_mfma_f32_16x16x32_bf16 v[58:61], v[164:167], v[196:199], v[58:61]
	v_mfma_f32_16x16x32_bf16 v[46:49], v[156:159], v[204:207], v[46:49]
	v_mfma_f32_16x16x32_bf16 v[42:45], v[164:167], v[204:207], v[42:45]
	v_mfma_f32_16x16x32_bf16 v[30:33], v[156:159], v[212:215], v[30:33]
	v_mfma_f32_16x16x32_bf16 v[26:29], v[164:167], v[212:215], v[26:29]
	v_mfma_f32_16x16x32_bf16 v[14:17], v[156:159], v[220:223], v[14:17]
	v_mfma_f32_16x16x32_bf16 v[10:13], v[164:167], v[220:223], v[10:13]
	s_setprio 0
	s_setprio 1
	v_mfma_f32_16x16x32_bf16 v[54:57], v[168:171], v[188:191], v[54:57]
	v_mfma_f32_16x16x32_bf16 v[50:53], v[180:183], v[188:191], v[50:53]
	v_mfma_f32_16x16x32_bf16 v[38:41], v[168:171], v[200:203], v[38:41]
	v_mfma_f32_16x16x32_bf16 v[34:37], v[180:183], v[200:203], v[34:37]
	v_mfma_f32_16x16x32_bf16 v[22:25], v[168:171], v[208:211], v[22:25]
	v_mfma_f32_16x16x32_bf16 v[18:21], v[180:183], v[208:211], v[18:21]
	v_mfma_f32_16x16x32_bf16 v[6:9], v[168:171], v[216:219], v[6:9]
	v_mfma_f32_16x16x32_bf16 v[2:5], v[180:183], v[216:219], v[2:5]
	v_mfma_f32_16x16x32_bf16 v[54:57], v[172:175], v[196:199], v[54:57]
	v_mfma_f32_16x16x32_bf16 v[50:53], v[184:187], v[196:199], v[50:53]
	v_mfma_f32_16x16x32_bf16 v[38:41], v[172:175], v[204:207], v[38:41]
	v_mfma_f32_16x16x32_bf16 v[34:37], v[184:187], v[204:207], v[34:37]
	v_mfma_f32_16x16x32_bf16 v[22:25], v[172:175], v[212:215], v[22:25]
	v_mfma_f32_16x16x32_bf16 v[18:21], v[184:187], v[212:215], v[18:21]
	v_mfma_f32_16x16x32_bf16 v[6:9], v[172:175], v[220:223], v[6:9]
	v_mfma_f32_16x16x32_bf16 v[2:5], v[184:187], v[220:223], v[2:5]
	s_setprio 0
	s_barrier
	s_add_i32 s64, s64, 2
	s_add_u32 s26, s26, 0x10000
	s_addc_u32 s27, s27, 0
	s_add_u32 s62, s62, 0x10000
	s_addc_u32 s63, s63, 0
	s_cmpk_gt_u32 s64, 0xa9
	s_cbranch_scc0 .LBB0_924
	s_and_b64 vcc, exec, s[16:17]
	s_cbranch_vccz .LBB0_927
	s_barrier
